# SwiGLU epilogue: rs^2 folded into the reciprocal argument (one packed multiply less per output pair)
# speedup vs baseline: 1.0078x; 1.0078x over previous
.Llast_0:
	v_add_u32_e32 v153, s64, v147
	ds_read_b128 v[160:163], v153
	v_xor_b32_e32 v253, 64, v153
	ds_read_b128 v[164:167], v253
	ds_read_b128 v[168:171], v153 offset:2048
	ds_read_b128 v[172:175], v253 offset:2048
	v_add_u32_e32 v153, s65, v147
	ds_read_b128 v[176:179], v153
	v_xor_b32_e32 v253, 64, v153
	ds_read_b128 v[180:183], v253
	ds_read_b128 v[186:189], v153 offset:2048
	ds_read_b128 v[190:193], v253 offset:2048
	s_add_u32 s48, s44, 0xfffc0080
	s_addc_u32 s49, s45, -1
	s_and_b64 s[46:47], s[46:47], exec
	s_cselect_b32 s49, s27, s49
	s_cselect_b32 s48, s68, s48
	s_cselect_b32 s47, s69, s74
	s_cselect_b32 s46, s70, s71
	v_lshl_add_u64 v[154:155], s[44:45], 0, v[138:139]
	s_add_i32 m0, s55, 0xc000
	ds_read_b128 v[194:197], v150
	v_xor_b32_e32 v253, 64, v150
	ds_read_b128 v[198:201], v253
	ds_read_b128 v[202:205], v150 offset:2048
	ds_read_b128 v[206:209], v253 offset:2048
	ds_read_b128 v[210:213], v150 offset:4096
	ds_read_b128 v[214:217], v253 offset:4096
	ds_read_b128 v[218:221], v150 offset:6144
	ds_read_b128 v[222:225], v253 offset:6144
	global_load_lds_dwordx4 v[154:155], off
	v_lshl_add_u64 v[154:155], s[44:45], 0, v[136:137]
	s_add_i32 m0, s55, 0xe000
	s_nop 0
	global_load_lds_dwordx4 v[154:155], off
	s_waitcnt vmcnt(8)
	s_waitcnt lgkmcnt(0)
	s_barrier
	s_setprio 1
	s_waitcnt lgkmcnt(0)
	v_mfma_f32_16x16x32_bf16 v[124:127], v[160:163], v[194:197], v[124:127]
	v_mfma_f32_16x16x32_bf16 v[124:127], v[164:167], v[198:201], v[124:127]
	v_mfma_f32_16x16x32_bf16 v[116:119], v[172:175], v[198:201], v[116:119]
	v_mfma_f32_16x16x32_bf16 v[116:119], v[168:171], v[194:197], v[116:119]
	v_mfma_f32_16x16x32_bf16 v[100:103], v[168:171], v[202:205], v[100:103]
	v_mfma_f32_16x16x32_bf16 v[100:103], v[172:175], v[206:209], v[100:103]
	v_mfma_f32_16x16x32_bf16 v[108:111], v[164:167], v[206:209], v[108:111]
	v_mfma_f32_16x16x32_bf16 v[108:111], v[160:163], v[202:205], v[108:111]
	v_mfma_f32_16x16x32_bf16 v[92:95], v[160:163], v[210:213], v[92:95]
	v_mfma_f32_16x16x32_bf16 v[92:95], v[164:167], v[214:217], v[92:95]
	v_mfma_f32_16x16x32_bf16 v[84:87], v[172:175], v[214:217], v[84:87]
	v_mfma_f32_16x16x32_bf16 v[84:87], v[168:171], v[210:213], v[84:87]
	v_mfma_f32_16x16x32_bf16 v[68:71], v[168:171], v[218:221], v[68:71]
	v_mfma_f32_16x16x32_bf16 v[68:71], v[172:175], v[222:225], v[68:71]
	v_mfma_f32_16x16x32_bf16 v[76:79], v[164:167], v[222:225], v[76:79]
	v_mfma_f32_16x16x32_bf16 v[76:79], v[160:163], v[218:221], v[76:79]
	s_setprio 0
	s_setprio 1
	v_mfma_f32_16x16x32_bf16 v[120:123], v[176:179], v[194:197], v[120:123]
	v_mfma_f32_16x16x32_bf16 v[120:123], v[180:183], v[198:201], v[120:123]
	v_mfma_f32_16x16x32_bf16 v[112:115], v[190:193], v[198:201], v[112:115]
	v_mfma_f32_16x16x32_bf16 v[112:115], v[186:189], v[194:197], v[112:115]
	v_mfma_f32_16x16x32_bf16 v[96:99], v[186:189], v[202:205], v[96:99]
	v_mfma_f32_16x16x32_bf16 v[96:99], v[190:193], v[206:209], v[96:99]
	v_mfma_f32_16x16x32_bf16 v[104:107], v[180:183], v[206:209], v[104:107]
	v_mfma_f32_16x16x32_bf16 v[104:107], v[176:179], v[202:205], v[104:107]
	v_mfma_f32_16x16x32_bf16 v[88:91], v[176:179], v[210:213], v[88:91]
	v_mfma_f32_16x16x32_bf16 v[88:91], v[180:183], v[214:217], v[88:91]
	v_mfma_f32_16x16x32_bf16 v[80:83], v[190:193], v[214:217], v[80:83]
	v_mfma_f32_16x16x32_bf16 v[80:83], v[186:189], v[210:213], v[80:83]
	v_mfma_f32_16x16x32_bf16 v[64:67], v[186:189], v[218:221], v[64:67]
	v_mfma_f32_16x16x32_bf16 v[64:67], v[190:193], v[222:225], v[64:67]
	v_mfma_f32_16x16x32_bf16 v[72:75], v[180:183], v[222:225], v[72:75]
	v_mfma_f32_16x16x32_bf16 v[72:75], v[176:179], v[218:221], v[72:75]
	s_setprio 0
	s_barrier
	s_add_i32 s76, s64, s52
	v_lshl_add_u64 v[154:155], s[46:47], 0, v[132:133]
	s_mov_b32 m0, s76
	ds_read_b128 v[194:197], v150 offset:16384
	v_xor_b32_e32 v253, 64, v150
	ds_read_b128 v[198:201], v253 offset:16384
	ds_read_b128 v[202:205], v150 offset:18432
	ds_read_b128 v[206:209], v253 offset:18432
	ds_read_b128 v[210:213], v150 offset:20480
	ds_read_b128 v[214:217], v253 offset:20480
	ds_read_b128 v[218:221], v150 offset:22528
	ds_read_b128 v[222:225], v253 offset:22528
	global_load_lds_dwordx4 v[154:155], off
	s_add_i32 m0, s76, 0x2000
	s_add_u32 s76, s46, 0x40000
	v_lshl_add_u64 v[226:227], s[46:47], 0, v[128:129]
	s_addc_u32 s77, s47, 0
	s_add_i32 s78, s65, s52
	global_load_lds_dwordx4 v[226:227], off
	v_lshl_add_u64 v[228:229], s[76:77], 0, v[132:133]
	s_mov_b32 m0, s78
	v_lshl_add_u64 v[230:231], s[48:49], 0, v[130:131]
	global_load_lds_dwordx4 v[228:229], off
	v_lshl_add_u64 v[228:229], s[76:77], 0, v[128:129]
	s_add_i32 m0, s78, 0x2000
	s_nop 0
	global_load_lds_dwordx4 v[228:229], off
	v_lshl_add_u64 v[228:229], s[48:49], 0, v[134:135]
	s_mov_b32 m0, s55
	s_nop 0
	global_load_lds_dwordx4 v[228:229], off
	s_mov_b32 m0, s56
	s_nop 0
	global_load_lds_dwordx4 v[230:231], off
	s_waitcnt vmcnt(8)
	s_waitcnt lgkmcnt(0)
	s_barrier
	s_setprio 1
	s_waitcnt lgkmcnt(0)
	v_mfma_f32_16x16x32_bf16 v[60:63], v[160:163], v[194:197], v[60:63]
	v_mfma_f32_16x16x32_bf16 v[60:63], v[164:167], v[198:201], v[60:63]
	v_mfma_f32_16x16x32_bf16 v[52:55], v[172:175], v[198:201], v[52:55]
	v_mfma_f32_16x16x32_bf16 v[52:55], v[168:171], v[194:197], v[52:55]
	v_mfma_f32_16x16x32_bf16 v[36:39], v[168:171], v[202:205], v[36:39]
	v_mfma_f32_16x16x32_bf16 v[36:39], v[172:175], v[206:209], v[36:39]
	v_mfma_f32_16x16x32_bf16 v[44:47], v[164:167], v[206:209], v[44:47]
	v_mfma_f32_16x16x32_bf16 v[44:47], v[160:163], v[202:205], v[44:47]
	v_mfma_f32_16x16x32_bf16 v[28:31], v[160:163], v[210:213], v[28:31]
	v_mfma_f32_16x16x32_bf16 v[28:31], v[164:167], v[214:217], v[28:31]
	v_mfma_f32_16x16x32_bf16 v[20:23], v[172:175], v[214:217], v[20:23]
	v_mfma_f32_16x16x32_bf16 v[20:23], v[168:171], v[210:213], v[20:23]
	v_mfma_f32_16x16x32_bf16 v[4:7], v[168:171], v[218:221], v[4:7]
	v_mfma_f32_16x16x32_bf16 v[4:7], v[172:175], v[222:225], v[4:7]
	v_mfma_f32_16x16x32_bf16 v[12:15], v[164:167], v[222:225], v[12:15]
	v_mfma_f32_16x16x32_bf16 v[12:15], v[160:163], v[218:221], v[12:15]
	s_setprio 0
	s_setprio 1
	v_mfma_f32_16x16x32_bf16 v[56:59], v[176:179], v[194:197], v[56:59]
	v_mfma_f32_16x16x32_bf16 v[56:59], v[180:183], v[198:201], v[56:59]
	v_mfma_f32_16x16x32_bf16 v[48:51], v[190:193], v[198:201], v[48:51]
	v_mfma_f32_16x16x32_bf16 v[48:51], v[186:189], v[194:197], v[48:51]
	v_mfma_f32_16x16x32_bf16 v[32:35], v[186:189], v[202:205], v[32:35]
	v_mfma_f32_16x16x32_bf16 v[32:35], v[190:193], v[206:209], v[32:35]
	v_mfma_f32_16x16x32_bf16 v[40:43], v[180:183], v[206:209], v[40:43]
	v_mfma_f32_16x16x32_bf16 v[40:43], v[176:179], v[202:205], v[40:43]
	v_mfma_f32_16x16x32_bf16 v[24:27], v[176:179], v[210:213], v[24:27]
	v_mfma_f32_16x16x32_bf16 v[24:27], v[180:183], v[214:217], v[24:27]
	v_mfma_f32_16x16x32_bf16 v[16:19], v[190:193], v[214:217], v[16:19]
	v_mfma_f32_16x16x32_bf16 v[16:19], v[186:189], v[210:213], v[16:19]
	v_mfma_f32_16x16x32_bf16 v[0:3], v[186:189], v[218:221], v[0:3]
	v_mfma_f32_16x16x32_bf16 v[0:3], v[190:193], v[222:225], v[0:3]
	v_mfma_f32_16x16x32_bf16 v[8:11], v[180:183], v[222:225], v[8:11]
	v_mfma_f32_16x16x32_bf16 v[8:11], v[176:179], v[218:221], v[8:11]
	s_setprio 0
	s_barrier
	s_add_i32 s76, 0, 0x18000
	v_add_u32_e32 v153, s76, v147
	s_add_i32 s77, 0, 0x1c000
	ds_read_b128 v[160:163], v153
	v_xor_b32_e32 v253, 64, v153
	ds_read_b128 v[164:167], v253
	ds_read_b128 v[168:171], v153 offset:2048
	ds_read_b128 v[172:175], v253 offset:2048
	v_add_u32_e32 v153, s77, v147
	ds_read_b128 v[176:179], v153
	v_xor_b32_e32 v253, 64, v153
	ds_read_b128 v[180:183], v253
	ds_read_b128 v[186:189], v153 offset:2048
	ds_read_b128 v[190:193], v253 offset:2048
	s_add_u32 s48, s48, 0x40000
	s_addc_u32 s49, s49, 0
	s_mov_b32 m0, s57
	v_lshl_add_u64 v[232:233], s[48:49], 0, v[134:135]
	ds_read_b128 v[194:197], v150 offset:32768
	v_xor_b32_e32 v253, 64, v150
	ds_read_b128 v[198:201], v253 offset:32768
	ds_read_b128 v[202:205], v150 offset:34816
	ds_read_b128 v[206:209], v253 offset:34816
	ds_read_b128 v[210:213], v150 offset:36864
	ds_read_b128 v[214:217], v253 offset:36864
	ds_read_b128 v[218:221], v150 offset:38912
	ds_read_b128 v[222:225], v253 offset:38912
	global_load_lds_dwordx4 v[232:233], off
	v_lshl_add_u64 v[232:233], s[48:49], 0, v[130:131]
	s_mov_b32 m0, s58
	s_nop 0
	global_load_lds_dwordx4 v[232:233], off
	s_waitcnt vmcnt(8)
	s_waitcnt lgkmcnt(0)
	s_barrier
	s_setprio 1
	s_waitcnt lgkmcnt(0)
	v_mfma_f32_16x16x32_bf16 v[124:127], v[160:163], v[194:197], v[124:127]
	v_mfma_f32_16x16x32_bf16 v[124:127], v[164:167], v[198:201], v[124:127]
	v_mfma_f32_16x16x32_bf16 v[116:119], v[172:175], v[198:201], v[116:119]
	v_mfma_f32_16x16x32_bf16 v[116:119], v[168:171], v[194:197], v[116:119]
	v_mfma_f32_16x16x32_bf16 v[100:103], v[168:171], v[202:205], v[100:103]
	v_mfma_f32_16x16x32_bf16 v[100:103], v[172:175], v[206:209], v[100:103]
	v_mfma_f32_16x16x32_bf16 v[108:111], v[164:167], v[206:209], v[108:111]
	v_mfma_f32_16x16x32_bf16 v[108:111], v[160:163], v[202:205], v[108:111]
	v_mfma_f32_16x16x32_bf16 v[92:95], v[160:163], v[210:213], v[92:95]
	v_mfma_f32_16x16x32_bf16 v[92:95], v[164:167], v[214:217], v[92:95]
	v_mfma_f32_16x16x32_bf16 v[84:87], v[172:175], v[214:217], v[84:87]
	v_mfma_f32_16x16x32_bf16 v[84:87], v[168:171], v[210:213], v[84:87]
	v_mfma_f32_16x16x32_bf16 v[68:71], v[168:171], v[218:221], v[68:71]
	v_mfma_f32_16x16x32_bf16 v[68:71], v[172:175], v[222:225], v[68:71]
	v_mfma_f32_16x16x32_bf16 v[76:79], v[164:167], v[222:225], v[76:79]
	v_mfma_f32_16x16x32_bf16 v[76:79], v[160:163], v[218:221], v[76:79]
	s_setprio 0
	s_setprio 1
	v_mfma_f32_16x16x32_bf16 v[120:123], v[176:179], v[194:197], v[120:123]
	v_mfma_f32_16x16x32_bf16 v[120:123], v[180:183], v[198:201], v[120:123]
	v_mfma_f32_16x16x32_bf16 v[112:115], v[190:193], v[198:201], v[112:115]
	v_mfma_f32_16x16x32_bf16 v[112:115], v[186:189], v[194:197], v[112:115]
	v_mfma_f32_16x16x32_bf16 v[96:99], v[186:189], v[202:205], v[96:99]
	v_mfma_f32_16x16x32_bf16 v[96:99], v[190:193], v[206:209], v[96:99]
	v_mfma_f32_16x16x32_bf16 v[104:107], v[180:183], v[206:209], v[104:107]
	v_mfma_f32_16x16x32_bf16 v[104:107], v[176:179], v[202:205], v[104:107]
	v_mfma_f32_16x16x32_bf16 v[88:91], v[176:179], v[210:213], v[88:91]
	v_mfma_f32_16x16x32_bf16 v[88:91], v[180:183], v[214:217], v[88:91]
	v_mfma_f32_16x16x32_bf16 v[80:83], v[190:193], v[214:217], v[80:83]
	v_mfma_f32_16x16x32_bf16 v[80:83], v[186:189], v[210:213], v[80:83]
	v_mfma_f32_16x16x32_bf16 v[64:67], v[186:189], v[218:221], v[64:67]
	v_mfma_f32_16x16x32_bf16 v[64:67], v[190:193], v[222:225], v[64:67]
	v_mfma_f32_16x16x32_bf16 v[72:75], v[180:183], v[222:225], v[72:75]
	v_mfma_f32_16x16x32_bf16 v[72:75], v[176:179], v[218:221], v[72:75]
	s_setprio 0
	s_barrier
	v_add_u32_e32 v234, 0x21000, v151
	ds_read_b128 v[236:239], v234
	ds_read_b128 v[240:243], v234 offset:256
	ds_read_b128 v[244:247], v234 offset:512
	ds_read_b128 v[248:251], v234 offset:768
	v_add_u32_e32 v235, s23, v146
	v_mul_u32_u24_e32 v235, 0x1600, v235
	v_lshl_or_b32 v234, s67, 7, v149
	v_lshl_add_u32 v235, v234, 1, v235
	s_add_i32 s48, s76, s52
	v_lshl_add_u64 v[154:155], v[154:155], 0, s[14:15]
	s_mov_b32 m0, s48
	ds_read_b128 v[194:197], v150 offset:49152
	v_xor_b32_e32 v253, 64, v150
	ds_read_b128 v[198:201], v253 offset:49152
	ds_read_b128 v[202:205], v150 offset:51200
	ds_read_b128 v[206:209], v253 offset:51200
	ds_read_b128 v[210:213], v150 offset:53248
	ds_read_b128 v[214:217], v253 offset:53248
	ds_read_b128 v[218:221], v150 offset:55296
	ds_read_b128 v[222:225], v253 offset:55296
	global_load_lds_dwordx4 v[154:155], off
	s_add_i32 m0, s48, 0x2000
	s_add_u32 s46, s46, 0x40080
	v_lshl_add_u64 v[154:155], v[226:227], 0, s[14:15]
	s_addc_u32 s47, s47, 0
	s_add_i32 s48, s77, s52
	global_load_lds_dwordx4 v[154:155], off
	v_lshl_add_u64 v[154:155], s[46:47], 0, v[132:133]
	s_mov_b32 m0, s48
	s_nop 0
	global_load_lds_dwordx4 v[154:155], off
	v_lshl_add_u64 v[154:155], s[46:47], 0, v[128:129]
	s_add_i32 m0, s48, 0x2000
	s_nop 0
	global_load_lds_dwordx4 v[154:155], off
	v_lshl_add_u64 v[154:155], v[228:229], 0, s[14:15]
	s_mov_b32 m0, s60
	s_nop 0
	global_load_lds_dwordx4 v[154:155], off
	v_lshl_add_u64 v[154:155], v[230:231], 0, s[14:15]
	s_mov_b32 m0, s61
	s_nop 0
	global_load_lds_dwordx4 v[154:155], off
	s_waitcnt lgkmcnt(8)
	v_add_f32_e32 v236, v236, v237
	v_add_f32_e32 v238, v238, v239
	v_add_f32_e32 v240, v240, v241
	v_add_f32_e32 v242, v242, v243
	v_add_f32_e32 v244, v244, v245
	v_add_f32_e32 v246, v246, v247
	v_add_f32_e32 v248, v248, v249
	v_add_f32_e32 v250, v250, v251
	v_add_f32_e32 v236, v236, v238
	v_add_f32_e32 v240, v240, v242
	v_add_f32_e32 v244, v244, v246
	v_add_f32_e32 v248, v248, v250
	v_fmamk_f32 v236, v236, 0x3a800000, v152
	v_fmamk_f32 v240, v240, 0x3a800000, v152
	v_fmamk_f32 v244, v244, 0x3a800000, v152
	v_fmamk_f32 v248, v248, 0x3a800000, v152
	v_rsq_f32_e32 v236, v236
	v_rsq_f32_e32 v240, v240
	v_rsq_f32_e32 v244, v244
	v_rsq_f32_e32 v248, v248
	v_mul_f32_e32 v252, 0xbfb8aa3b, v236
	v_mul_f32_e32 v254, v236, v236
	v_rcp_f32_e32 v254, v254
	v_pk_mul_f32 v[120:121], v[124:125], v[120:121]
	v_pk_mul_f32 v[122:123], v[126:127], v[122:123]
	v_pk_mul_f32 v[112:113], v[116:117], v[112:113]
	v_pk_mul_f32 v[114:115], v[118:119], v[114:115]
	v_pk_mul_f32 v[124:125], v[124:125], v[252:253] op_sel_hi:[1,0]
	v_pk_mul_f32 v[126:127], v[126:127], v[252:253] op_sel_hi:[1,0]
	v_pk_mul_f32 v[116:117], v[116:117], v[252:253] op_sel_hi:[1,0]
	v_pk_mul_f32 v[118:119], v[118:119], v[252:253] op_sel_hi:[1,0]
	v_exp_f32_e32 v124, v124
	v_exp_f32_e32 v125, v125
	v_exp_f32_e32 v126, v126
	v_exp_f32_e32 v127, v127
	v_exp_f32_e32 v116, v116
	v_exp_f32_e32 v117, v117
	v_exp_f32_e32 v118, v118
	v_exp_f32_e32 v119, v119
	v_pk_fma_f32 v[124:125], v[124:125], v[254:255], v[254:255] op_sel_hi:[1,0,0]
	v_pk_fma_f32 v[126:127], v[126:127], v[254:255], v[254:255] op_sel_hi:[1,0,0]
	v_pk_fma_f32 v[116:117], v[116:117], v[254:255], v[254:255] op_sel_hi:[1,0,0]
	v_pk_fma_f32 v[118:119], v[118:119], v[254:255], v[254:255] op_sel_hi:[1,0,0]
	v_rcp_f32_e32 v124, v124
	v_rcp_f32_e32 v125, v125
	v_rcp_f32_e32 v126, v126
	v_rcp_f32_e32 v127, v127
	v_rcp_f32_e32 v116, v116
	v_rcp_f32_e32 v117, v117
	v_rcp_f32_e32 v118, v118
	v_rcp_f32_e32 v119, v119
	v_pk_mul_f32 v[120:121], v[120:121], v[124:125]
	v_pk_mul_f32 v[122:123], v[122:123], v[126:127]
	v_pk_mul_f32 v[112:113], v[112:113], v[116:117]
	v_pk_mul_f32 v[114:115], v[114:115], v[118:119]
	v_cvt_pk_bf16_f32 v120, v120, v121
	v_cvt_pk_bf16_f32 v121, v122, v123
	v_cvt_pk_bf16_f32 v122, v112, v113
	v_cvt_pk_bf16_f32 v123, v114, v115
	global_store_dwordx4 v235, v[120:123], s[10:11]
	v_add_u32_e32 v234, 0x16000, v235
	v_mul_f32_e32 v252, 0xbfb8aa3b, v240
	v_mul_f32_e32 v254, v240, v240
	v_rcp_f32_e32 v254, v254
	v_pk_mul_f32 v[104:105], v[108:109], v[104:105]
	v_pk_mul_f32 v[106:107], v[110:111], v[106:107]
	v_pk_mul_f32 v[96:97], v[100:101], v[96:97]
	v_pk_mul_f32 v[98:99], v[102:103], v[98:99]
	v_pk_mul_f32 v[108:109], v[108:109], v[252:253] op_sel_hi:[1,0]
	v_pk_mul_f32 v[110:111], v[110:111], v[252:253] op_sel_hi:[1,0]
	v_pk_mul_f32 v[100:101], v[100:101], v[252:253] op_sel_hi:[1,0]
	v_pk_mul_f32 v[102:103], v[102:103], v[252:253] op_sel_hi:[1,0]
	v_exp_f32_e32 v108, v108
	v_exp_f32_e32 v109, v109
	v_exp_f32_e32 v110, v110
	v_exp_f32_e32 v111, v111
	v_exp_f32_e32 v100, v100
	v_exp_f32_e32 v101, v101
	v_exp_f32_e32 v102, v102
	v_exp_f32_e32 v103, v103
	v_pk_fma_f32 v[108:109], v[108:109], v[254:255], v[254:255] op_sel_hi:[1,0,0]
	v_pk_fma_f32 v[110:111], v[110:111], v[254:255], v[254:255] op_sel_hi:[1,0,0]
	v_pk_fma_f32 v[100:101], v[100:101], v[254:255], v[254:255] op_sel_hi:[1,0,0]
	v_pk_fma_f32 v[102:103], v[102:103], v[254:255], v[254:255] op_sel_hi:[1,0,0]
	v_rcp_f32_e32 v108, v108
	v_rcp_f32_e32 v109, v109
	v_rcp_f32_e32 v110, v110
	v_rcp_f32_e32 v111, v111
	v_rcp_f32_e32 v100, v100
	v_rcp_f32_e32 v101, v101
	v_rcp_f32_e32 v102, v102
	v_rcp_f32_e32 v103, v103
	v_pk_mul_f32 v[104:105], v[104:105], v[108:109]
	v_pk_mul_f32 v[106:107], v[106:107], v[110:111]
	v_pk_mul_f32 v[96:97], v[96:97], v[100:101]
	v_pk_mul_f32 v[98:99], v[98:99], v[102:103]
	v_cvt_pk_bf16_f32 v104, v104, v105
	v_cvt_pk_bf16_f32 v105, v106, v107
	v_cvt_pk_bf16_f32 v106, v96, v97
	v_cvt_pk_bf16_f32 v107, v98, v99
	global_store_dwordx4 v234, v[104:107], s[10:11]
	v_add_u32_e32 v235, 0x16000, v234
	v_mul_f32_e32 v252, 0xbfb8aa3b, v244
	v_mul_f32_e32 v254, v244, v244
	v_rcp_f32_e32 v254, v254
	v_pk_mul_f32 v[88:89], v[92:93], v[88:89]
	v_pk_mul_f32 v[90:91], v[94:95], v[90:91]
	v_pk_mul_f32 v[80:81], v[84:85], v[80:81]
	v_pk_mul_f32 v[82:83], v[86:87], v[82:83]
	v_pk_mul_f32 v[92:93], v[92:93], v[252:253] op_sel_hi:[1,0]
	v_pk_mul_f32 v[94:95], v[94:95], v[252:253] op_sel_hi:[1,0]
	v_pk_mul_f32 v[84:85], v[84:85], v[252:253] op_sel_hi:[1,0]
	v_pk_mul_f32 v[86:87], v[86:87], v[252:253] op_sel_hi:[1,0]
	v_exp_f32_e32 v92, v92
	v_exp_f32_e32 v93, v93
	v_exp_f32_e32 v94, v94
	v_exp_f32_e32 v95, v95
	v_exp_f32_e32 v84, v84
	v_exp_f32_e32 v85, v85
	v_exp_f32_e32 v86, v86
	v_exp_f32_e32 v87, v87
	v_pk_fma_f32 v[92:93], v[92:93], v[254:255], v[254:255] op_sel_hi:[1,0,0]
	v_pk_fma_f32 v[94:95], v[94:95], v[254:255], v[254:255] op_sel_hi:[1,0,0]
	v_pk_fma_f32 v[84:85], v[84:85], v[254:255], v[254:255] op_sel_hi:[1,0,0]
	v_pk_fma_f32 v[86:87], v[86:87], v[254:255], v[254:255] op_sel_hi:[1,0,0]
	v_rcp_f32_e32 v92, v92
	v_rcp_f32_e32 v93, v93
	v_rcp_f32_e32 v94, v94
	v_rcp_f32_e32 v95, v95
	v_rcp_f32_e32 v84, v84
	v_rcp_f32_e32 v85, v85
	v_rcp_f32_e32 v86, v86
	v_rcp_f32_e32 v87, v87
	v_pk_mul_f32 v[88:89], v[88:89], v[92:93]
	v_pk_mul_f32 v[90:91], v[90:91], v[94:95]
	v_pk_mul_f32 v[80:81], v[80:81], v[84:85]
	v_pk_mul_f32 v[82:83], v[82:83], v[86:87]
	v_cvt_pk_bf16_f32 v88, v88, v89
	v_cvt_pk_bf16_f32 v89, v90, v91
	v_cvt_pk_bf16_f32 v90, v80, v81
	v_cvt_pk_bf16_f32 v91, v82, v83
	global_store_dwordx4 v235, v[88:91], s[10:11]
	v_add_u32_e32 v234, 0x16000, v235
	v_mul_f32_e32 v252, 0xbfb8aa3b, v248
	v_mul_f32_e32 v254, v248, v248
	v_rcp_f32_e32 v254, v254
	v_pk_mul_f32 v[72:73], v[76:77], v[72:73]
	v_pk_mul_f32 v[74:75], v[78:79], v[74:75]
	v_pk_mul_f32 v[64:65], v[68:69], v[64:65]
	v_pk_mul_f32 v[66:67], v[70:71], v[66:67]
	v_pk_mul_f32 v[76:77], v[76:77], v[252:253] op_sel_hi:[1,0]
	v_pk_mul_f32 v[78:79], v[78:79], v[252:253] op_sel_hi:[1,0]
	v_pk_mul_f32 v[68:69], v[68:69], v[252:253] op_sel_hi:[1,0]
	v_pk_mul_f32 v[70:71], v[70:71], v[252:253] op_sel_hi:[1,0]
	v_exp_f32_e32 v76, v76
	v_exp_f32_e32 v77, v77
	v_exp_f32_e32 v78, v78
	v_exp_f32_e32 v79, v79
	v_exp_f32_e32 v68, v68
	v_exp_f32_e32 v69, v69
	v_exp_f32_e32 v70, v70
	v_exp_f32_e32 v71, v71
	v_pk_fma_f32 v[76:77], v[76:77], v[254:255], v[254:255] op_sel_hi:[1,0,0]
	v_pk_fma_f32 v[78:79], v[78:79], v[254:255], v[254:255] op_sel_hi:[1,0,0]
	v_pk_fma_f32 v[68:69], v[68:69], v[254:255], v[254:255] op_sel_hi:[1,0,0]
	v_pk_fma_f32 v[70:71], v[70:71], v[254:255], v[254:255] op_sel_hi:[1,0,0]
	v_rcp_f32_e32 v76, v76
	v_rcp_f32_e32 v77, v77
	v_rcp_f32_e32 v78, v78
	v_rcp_f32_e32 v79, v79
	v_rcp_f32_e32 v68, v68
	v_rcp_f32_e32 v69, v69
	v_rcp_f32_e32 v70, v70
	v_rcp_f32_e32 v71, v71
	v_pk_mul_f32 v[72:73], v[72:73], v[76:77]
	v_pk_mul_f32 v[74:75], v[74:75], v[78:79]
	v_pk_mul_f32 v[64:65], v[64:65], v[68:69]
	v_pk_mul_f32 v[66:67], v[66:67], v[70:71]
	v_cvt_pk_bf16_f32 v72, v72, v73
	v_cvt_pk_bf16_f32 v73, v74, v75
	v_cvt_pk_bf16_f32 v74, v64, v65
	v_cvt_pk_bf16_f32 v75, v66, v67
	global_store_dwordx4 v234, v[72:75], s[10:11]
	s_waitcnt vmcnt(12)
	s_waitcnt lgkmcnt(0)
	s_barrier
	s_setprio 1
	s_waitcnt lgkmcnt(0)
	v_mfma_f32_16x16x32_bf16 v[60:63], v[160:163], v[194:197], v[60:63]
	v_mfma_f32_16x16x32_bf16 v[60:63], v[164:167], v[198:201], v[60:63]
	v_mfma_f32_16x16x32_bf16 v[52:55], v[172:175], v[198:201], v[52:55]
	v_mfma_f32_16x16x32_bf16 v[52:55], v[168:171], v[194:197], v[52:55]
	v_mfma_f32_16x16x32_bf16 v[36:39], v[168:171], v[202:205], v[36:39]
	v_mfma_f32_16x16x32_bf16 v[36:39], v[172:175], v[206:209], v[36:39]
	v_mfma_f32_16x16x32_bf16 v[44:47], v[164:167], v[206:209], v[44:47]
	v_mfma_f32_16x16x32_bf16 v[44:47], v[160:163], v[202:205], v[44:47]
	v_mfma_f32_16x16x32_bf16 v[28:31], v[160:163], v[210:213], v[28:31]
	v_mfma_f32_16x16x32_bf16 v[28:31], v[164:167], v[214:217], v[28:31]
	v_mfma_f32_16x16x32_bf16 v[20:23], v[172:175], v[214:217], v[20:23]
	v_mfma_f32_16x16x32_bf16 v[20:23], v[168:171], v[210:213], v[20:23]
	v_mfma_f32_16x16x32_bf16 v[4:7], v[168:171], v[218:221], v[4:7]
	v_mfma_f32_16x16x32_bf16 v[4:7], v[172:175], v[222:225], v[4:7]
	v_mfma_f32_16x16x32_bf16 v[12:15], v[164:167], v[222:225], v[12:15]
	v_mfma_f32_16x16x32_bf16 v[12:15], v[160:163], v[218:221], v[12:15]
	s_setprio 0
	s_setprio 1
	v_mfma_f32_16x16x32_bf16 v[56:59], v[176:179], v[194:197], v[56:59]
	v_mfma_f32_16x16x32_bf16 v[56:59], v[180:183], v[198:201], v[56:59]
	v_mfma_f32_16x16x32_bf16 v[48:51], v[190:193], v[198:201], v[48:51]
	v_mfma_f32_16x16x32_bf16 v[48:51], v[186:189], v[194:197], v[48:51]
	v_mfma_f32_16x16x32_bf16 v[32:35], v[186:189], v[202:205], v[32:35]
	v_mfma_f32_16x16x32_bf16 v[32:35], v[190:193], v[206:209], v[32:35]
	v_mfma_f32_16x16x32_bf16 v[40:43], v[180:183], v[206:209], v[40:43]
	v_mfma_f32_16x16x32_bf16 v[40:43], v[176:179], v[202:205], v[40:43]
	v_mfma_f32_16x16x32_bf16 v[24:27], v[176:179], v[210:213], v[24:27]
	v_mfma_f32_16x16x32_bf16 v[24:27], v[180:183], v[214:217], v[24:27]
	v_mfma_f32_16x16x32_bf16 v[16:19], v[190:193], v[214:217], v[16:19]
	v_mfma_f32_16x16x32_bf16 v[16:19], v[186:189], v[210:213], v[16:19]
	v_mfma_f32_16x16x32_bf16 v[0:3], v[186:189], v[218:221], v[0:3]
	v_mfma_f32_16x16x32_bf16 v[0:3], v[190:193], v[222:225], v[0:3]
	v_mfma_f32_16x16x32_bf16 v[8:11], v[180:183], v[222:225], v[8:11]
	v_mfma_f32_16x16x32_bf16 v[8:11], v[176:179], v[218:221], v[8:11]
	s_setprio 0
	s_barrier
	s_add_i32 s75, s75, 2
	s_add_u32 s71, s71, 0x100
	s_addc_u32 s74, s74, 0
	s_add_u32 s44, s44, 0x100
	s_addc_u32 s45, s45, 0

.LBB0_80:
	v_add_u32_e32 v235, 0x84000, v235
	v_add_u32_e32 v234, 0x21800, v151
	ds_read_b128 v[236:239], v234
	ds_read_b128 v[240:243], v234 offset:256
	ds_read_b128 v[244:247], v234 offset:512
	ds_read_b128 v[248:251], v234 offset:768
	s_waitcnt lgkmcnt(0)
	v_add_f32_e32 v236, v236, v237
	v_add_f32_e32 v238, v238, v239
	v_add_f32_e32 v240, v240, v241
	v_add_f32_e32 v242, v242, v243
	v_add_f32_e32 v244, v244, v245
	v_add_f32_e32 v246, v246, v247
	v_add_f32_e32 v248, v248, v249
	v_add_f32_e32 v250, v250, v251
	v_add_f32_e32 v236, v236, v238
	v_add_f32_e32 v240, v240, v242
	v_add_f32_e32 v244, v244, v246
	v_add_f32_e32 v248, v248, v250
	v_fmamk_f32 v236, v236, 0x3a800000, v152
	v_fmamk_f32 v240, v240, 0x3a800000, v152
	v_fmamk_f32 v244, v244, 0x3a800000, v152
	v_fmamk_f32 v248, v248, 0x3a800000, v152
	v_rsq_f32_e32 v236, v236
	v_rsq_f32_e32 v240, v240
	v_rsq_f32_e32 v244, v244
	v_rsq_f32_e32 v248, v248
	v_mul_f32_e32 v252, 0xbfb8aa3b, v236
	v_mul_f32_e32 v254, v236, v236
	v_rcp_f32_e32 v254, v254
	v_pk_mul_f32 v[56:57], v[60:61], v[56:57]
	v_pk_mul_f32 v[58:59], v[62:63], v[58:59]
	v_pk_mul_f32 v[48:49], v[52:53], v[48:49]
	v_pk_mul_f32 v[50:51], v[54:55], v[50:51]
	v_pk_mul_f32 v[60:61], v[60:61], v[252:253] op_sel_hi:[1,0]
	v_pk_mul_f32 v[62:63], v[62:63], v[252:253] op_sel_hi:[1,0]
	v_pk_mul_f32 v[52:53], v[52:53], v[252:253] op_sel_hi:[1,0]
	v_pk_mul_f32 v[54:55], v[54:55], v[252:253] op_sel_hi:[1,0]
	v_exp_f32_e32 v60, v60
	v_exp_f32_e32 v61, v61
	v_exp_f32_e32 v62, v62
	v_exp_f32_e32 v63, v63
	v_exp_f32_e32 v52, v52
	v_exp_f32_e32 v53, v53
	v_exp_f32_e32 v54, v54
	v_exp_f32_e32 v55, v55
	v_pk_fma_f32 v[60:61], v[60:61], v[254:255], v[254:255] op_sel_hi:[1,0,0]
	v_pk_fma_f32 v[62:63], v[62:63], v[254:255], v[254:255] op_sel_hi:[1,0,0]
	v_pk_fma_f32 v[52:53], v[52:53], v[254:255], v[254:255] op_sel_hi:[1,0,0]
	v_pk_fma_f32 v[54:55], v[54:55], v[254:255], v[254:255] op_sel_hi:[1,0,0]
	v_rcp_f32_e32 v60, v60
	v_rcp_f32_e32 v61, v61
	v_rcp_f32_e32 v62, v62
	v_rcp_f32_e32 v63, v63
	v_rcp_f32_e32 v52, v52
	v_rcp_f32_e32 v53, v53
	v_rcp_f32_e32 v54, v54
	v_rcp_f32_e32 v55, v55
	v_pk_mul_f32 v[56:57], v[56:57], v[60:61]
	v_pk_mul_f32 v[58:59], v[58:59], v[62:63]
	v_pk_mul_f32 v[48:49], v[48:49], v[52:53]
	v_pk_mul_f32 v[50:51], v[50:51], v[54:55]
	v_cvt_pk_bf16_f32 v56, v56, v57
	v_cvt_pk_bf16_f32 v57, v58, v59
	v_cvt_pk_bf16_f32 v58, v48, v49
	v_cvt_pk_bf16_f32 v59, v50, v51
	global_store_dwordx4 v235, v[56:59], s[10:11]
	v_add_u32_e32 v234, 0x16000, v235
	v_mul_f32_e32 v252, 0xbfb8aa3b, v240
	v_mul_f32_e32 v254, v240, v240
	v_rcp_f32_e32 v254, v254
	v_pk_mul_f32 v[40:41], v[44:45], v[40:41]
	v_pk_mul_f32 v[42:43], v[46:47], v[42:43]
	v_pk_mul_f32 v[32:33], v[36:37], v[32:33]
	v_pk_mul_f32 v[34:35], v[38:39], v[34:35]
	v_pk_mul_f32 v[44:45], v[44:45], v[252:253] op_sel_hi:[1,0]
	v_pk_mul_f32 v[46:47], v[46:47], v[252:253] op_sel_hi:[1,0]
	v_pk_mul_f32 v[36:37], v[36:37], v[252:253] op_sel_hi:[1,0]
	v_pk_mul_f32 v[38:39], v[38:39], v[252:253] op_sel_hi:[1,0]
	v_exp_f32_e32 v44, v44
	v_exp_f32_e32 v45, v45
	v_exp_f32_e32 v46, v46
	v_exp_f32_e32 v47, v47
	v_exp_f32_e32 v36, v36
	v_exp_f32_e32 v37, v37
	v_exp_f32_e32 v38, v38
	v_exp_f32_e32 v39, v39
	v_pk_fma_f32 v[44:45], v[44:45], v[254:255], v[254:255] op_sel_hi:[1,0,0]
	v_pk_fma_f32 v[46:47], v[46:47], v[254:255], v[254:255] op_sel_hi:[1,0,0]
	v_pk_fma_f32 v[36:37], v[36:37], v[254:255], v[254:255] op_sel_hi:[1,0,0]
	v_pk_fma_f32 v[38:39], v[38:39], v[254:255], v[254:255] op_sel_hi:[1,0,0]
	v_rcp_f32_e32 v44, v44
	v_rcp_f32_e32 v45, v45
	v_rcp_f32_e32 v46, v46
	v_rcp_f32_e32 v47, v47
	v_rcp_f32_e32 v36, v36
	v_rcp_f32_e32 v37, v37
	v_rcp_f32_e32 v38, v38
	v_rcp_f32_e32 v39, v39
	v_pk_mul_f32 v[40:41], v[40:41], v[44:45]
	v_pk_mul_f32 v[42:43], v[42:43], v[46:47]
	v_pk_mul_f32 v[32:33], v[32:33], v[36:37]
	v_pk_mul_f32 v[34:35], v[34:35], v[38:39]
	v_cvt_pk_bf16_f32 v40, v40, v41
	v_cvt_pk_bf16_f32 v41, v42, v43
	v_cvt_pk_bf16_f32 v42, v32, v33
	v_cvt_pk_bf16_f32 v43, v34, v35
	global_store_dwordx4 v234, v[40:43], s[10:11]
	v_add_u32_e32 v235, 0x16000, v234
	v_mul_f32_e32 v252, 0xbfb8aa3b, v244
	v_mul_f32_e32 v254, v244, v244
	v_rcp_f32_e32 v254, v254
	v_pk_mul_f32 v[24:25], v[28:29], v[24:25]
	v_pk_mul_f32 v[26:27], v[30:31], v[26:27]
	v_pk_mul_f32 v[16:17], v[20:21], v[16:17]
	v_pk_mul_f32 v[18:19], v[22:23], v[18:19]
	v_pk_mul_f32 v[28:29], v[28:29], v[252:253] op_sel_hi:[1,0]
	v_pk_mul_f32 v[30:31], v[30:31], v[252:253] op_sel_hi:[1,0]
	v_pk_mul_f32 v[20:21], v[20:21], v[252:253] op_sel_hi:[1,0]
	v_pk_mul_f32 v[22:23], v[22:23], v[252:253] op_sel_hi:[1,0]
	v_exp_f32_e32 v28, v28
	v_exp_f32_e32 v29, v29
	v_exp_f32_e32 v30, v30
	v_exp_f32_e32 v31, v31
	v_exp_f32_e32 v20, v20
	v_exp_f32_e32 v21, v21
	v_exp_f32_e32 v22, v22
	v_exp_f32_e32 v23, v23
	v_pk_fma_f32 v[28:29], v[28:29], v[254:255], v[254:255] op_sel_hi:[1,0,0]
	v_pk_fma_f32 v[30:31], v[30:31], v[254:255], v[254:255] op_sel_hi:[1,0,0]
	v_pk_fma_f32 v[20:21], v[20:21], v[254:255], v[254:255] op_sel_hi:[1,0,0]
	v_pk_fma_f32 v[22:23], v[22:23], v[254:255], v[254:255] op_sel_hi:[1,0,0]
	v_rcp_f32_e32 v28, v28
	v_rcp_f32_e32 v29, v29
	v_rcp_f32_e32 v30, v30
	v_rcp_f32_e32 v31, v31
	v_rcp_f32_e32 v20, v20
	v_rcp_f32_e32 v21, v21
	v_rcp_f32_e32 v22, v22
	v_rcp_f32_e32 v23, v23
	v_pk_mul_f32 v[24:25], v[24:25], v[28:29]
	v_pk_mul_f32 v[26:27], v[26:27], v[30:31]
	v_pk_mul_f32 v[16:17], v[16:17], v[20:21]
	v_pk_mul_f32 v[18:19], v[18:19], v[22:23]
	v_cvt_pk_bf16_f32 v24, v24, v25
	v_cvt_pk_bf16_f32 v25, v26, v27
	v_cvt_pk_bf16_f32 v26, v16, v17
	v_cvt_pk_bf16_f32 v27, v18, v19
	global_store_dwordx4 v235, v[24:27], s[10:11]
	v_add_u32_e32 v234, 0x16000, v235
	v_mul_f32_e32 v252, 0xbfb8aa3b, v248
	v_mul_f32_e32 v254, v248, v248
	v_rcp_f32_e32 v254, v254
	v_pk_mul_f32 v[8:9], v[12:13], v[8:9]
	v_pk_mul_f32 v[10:11], v[14:15], v[10:11]
	v_pk_mul_f32 v[0:1], v[4:5], v[0:1]
	v_pk_mul_f32 v[2:3], v[6:7], v[2:3]
	v_pk_mul_f32 v[12:13], v[12:13], v[252:253] op_sel_hi:[1,0]
	v_pk_mul_f32 v[14:15], v[14:15], v[252:253] op_sel_hi:[1,0]
	v_pk_mul_f32 v[4:5], v[4:5], v[252:253] op_sel_hi:[1,0]
	v_pk_mul_f32 v[6:7], v[6:7], v[252:253] op_sel_hi:[1,0]
	v_exp_f32_e32 v12, v12
	v_exp_f32_e32 v13, v13
	v_exp_f32_e32 v14, v14
	v_exp_f32_e32 v15, v15
	v_exp_f32_e32 v4, v4
	v_exp_f32_e32 v5, v5
	v_exp_f32_e32 v6, v6
	v_exp_f32_e32 v7, v7
	v_pk_fma_f32 v[12:13], v[12:13], v[254:255], v[254:255] op_sel_hi:[1,0,0]
	v_pk_fma_f32 v[14:15], v[14:15], v[254:255], v[254:255] op_sel_hi:[1,0,0]
	v_pk_fma_f32 v[4:5], v[4:5], v[254:255], v[254:255] op_sel_hi:[1,0,0]
	v_pk_fma_f32 v[6:7], v[6:7], v[254:255], v[254:255] op_sel_hi:[1,0,0]
	v_rcp_f32_e32 v12, v12
	v_rcp_f32_e32 v13, v13
	v_rcp_f32_e32 v14, v14
	v_rcp_f32_e32 v15, v15
	v_rcp_f32_e32 v4, v4
	v_rcp_f32_e32 v5, v5
	v_rcp_f32_e32 v6, v6
	v_rcp_f32_e32 v7, v7
	v_pk_mul_f32 v[8:9], v[8:9], v[12:13]
	v_pk_mul_f32 v[10:11], v[10:11], v[14:15]
	v_pk_mul_f32 v[0:1], v[0:1], v[4:5]
	v_pk_mul_f32 v[2:3], v[2:3], v[6:7]
	v_cvt_pk_bf16_f32 v8, v8, v9
	v_cvt_pk_bf16_f32 v9, v10, v11
	v_cvt_pk_bf16_f32 v10, v0, v1
	v_cvt_pk_bf16_f32 v11, v2, v3
	global_store_dwordx4 v234, v[8:11], s[10:11]
	s_andn2_b64 vcc, exec, s[4:5]
	s_mov_b64 s[4:5], -1
	s_cbranch_vccnz .LBB0_71
	s_andn2_b64 vcc, exec, s[8:9]
	s_cbranch_vccnz .LBB0_70
	s_barrier
	s_branch .LBB0_70

.Llast_4:
	v_add_u32_e32 v153, s66, v147
	ds_read_b128 v[160:163], v153
	v_xor_b32_e32 v253, 64, v153
	ds_read_b128 v[164:167], v253
	ds_read_b128 v[168:171], v153 offset:2048
	ds_read_b128 v[172:175], v253 offset:2048
	v_add_u32_e32 v153, s67, v147
	ds_read_b128 v[176:179], v153
	v_xor_b32_e32 v253, 64, v153
	ds_read_b128 v[180:183], v253
	ds_read_b128 v[186:189], v153 offset:2048
	ds_read_b128 v[190:193], v253 offset:2048
	s_add_u32 s50, s46, 0xfffc0080
	s_addc_u32 s51, s47, -1
	s_and_b64 s[48:49], s[48:49], exec
	s_cselect_b32 s51, s29, s51
	s_cselect_b32 s50, s70, s50
	s_cselect_b32 s49, s71, s74
	s_cselect_b32 s48, s72, s73
	v_lshl_add_u64 v[154:155], s[46:47], 0, v[138:139]
	s_add_i32 m0, s57, 0xc000
	ds_read_b128 v[194:197], v150
	v_xor_b32_e32 v253, 64, v150
	ds_read_b128 v[198:201], v253
	ds_read_b128 v[202:205], v150 offset:2048
	ds_read_b128 v[206:209], v253 offset:2048
	ds_read_b128 v[210:213], v150 offset:4096
	ds_read_b128 v[214:217], v253 offset:4096
	ds_read_b128 v[218:221], v150 offset:6144
	ds_read_b128 v[222:225], v253 offset:6144
	global_load_lds_dwordx4 v[154:155], off
	v_lshl_add_u64 v[154:155], s[46:47], 0, v[136:137]
	s_add_i32 m0, s57, 0xe000
	s_nop 0
	global_load_lds_dwordx4 v[154:155], off
	s_waitcnt vmcnt(8)
	s_waitcnt lgkmcnt(0)
	s_barrier
	s_setprio 1
	s_waitcnt lgkmcnt(0)
	v_mfma_f32_16x16x32_bf16 v[124:127], v[160:163], v[194:197], v[124:127]
	v_mfma_f32_16x16x32_bf16 v[124:127], v[164:167], v[198:201], v[124:127]
	v_mfma_f32_16x16x32_bf16 v[116:119], v[172:175], v[198:201], v[116:119]
	v_mfma_f32_16x16x32_bf16 v[116:119], v[168:171], v[194:197], v[116:119]
	v_mfma_f32_16x16x32_bf16 v[100:103], v[168:171], v[202:205], v[100:103]
	v_mfma_f32_16x16x32_bf16 v[100:103], v[172:175], v[206:209], v[100:103]
	v_mfma_f32_16x16x32_bf16 v[108:111], v[164:167], v[206:209], v[108:111]
	v_mfma_f32_16x16x32_bf16 v[108:111], v[160:163], v[202:205], v[108:111]
	v_mfma_f32_16x16x32_bf16 v[92:95], v[160:163], v[210:213], v[92:95]
	v_mfma_f32_16x16x32_bf16 v[92:95], v[164:167], v[214:217], v[92:95]
	v_mfma_f32_16x16x32_bf16 v[84:87], v[172:175], v[214:217], v[84:87]
	v_mfma_f32_16x16x32_bf16 v[84:87], v[168:171], v[210:213], v[84:87]
	v_mfma_f32_16x16x32_bf16 v[68:71], v[168:171], v[218:221], v[68:71]
	v_mfma_f32_16x16x32_bf16 v[68:71], v[172:175], v[222:225], v[68:71]
	v_mfma_f32_16x16x32_bf16 v[76:79], v[164:167], v[222:225], v[76:79]
	v_mfma_f32_16x16x32_bf16 v[76:79], v[160:163], v[218:221], v[76:79]
	s_setprio 0
	s_setprio 1
	v_mfma_f32_16x16x32_bf16 v[120:123], v[176:179], v[194:197], v[120:123]
	v_mfma_f32_16x16x32_bf16 v[120:123], v[180:183], v[198:201], v[120:123]
	v_mfma_f32_16x16x32_bf16 v[112:115], v[190:193], v[198:201], v[112:115]
	v_mfma_f32_16x16x32_bf16 v[112:115], v[186:189], v[194:197], v[112:115]
	v_mfma_f32_16x16x32_bf16 v[96:99], v[186:189], v[202:205], v[96:99]
	v_mfma_f32_16x16x32_bf16 v[96:99], v[190:193], v[206:209], v[96:99]
	v_mfma_f32_16x16x32_bf16 v[104:107], v[180:183], v[206:209], v[104:107]
	v_mfma_f32_16x16x32_bf16 v[104:107], v[176:179], v[202:205], v[104:107]
	v_mfma_f32_16x16x32_bf16 v[88:91], v[176:179], v[210:213], v[88:91]
	v_mfma_f32_16x16x32_bf16 v[88:91], v[180:183], v[214:217], v[88:91]
	v_mfma_f32_16x16x32_bf16 v[80:83], v[190:193], v[214:217], v[80:83]
	v_mfma_f32_16x16x32_bf16 v[80:83], v[186:189], v[210:213], v[80:83]
	v_mfma_f32_16x16x32_bf16 v[64:67], v[186:189], v[218:221], v[64:67]
	v_mfma_f32_16x16x32_bf16 v[64:67], v[190:193], v[222:225], v[64:67]
	v_mfma_f32_16x16x32_bf16 v[72:75], v[180:183], v[222:225], v[72:75]
	v_mfma_f32_16x16x32_bf16 v[72:75], v[176:179], v[218:221], v[72:75]
	s_setprio 0
	s_barrier
	s_add_i32 s76, s66, s54
	v_lshl_add_u64 v[154:155], s[48:49], 0, v[132:133]
	s_mov_b32 m0, s76
	ds_read_b128 v[194:197], v150 offset:16384
	v_xor_b32_e32 v253, 64, v150
	ds_read_b128 v[198:201], v253 offset:16384
	ds_read_b128 v[202:205], v150 offset:18432
	ds_read_b128 v[206:209], v253 offset:18432
	ds_read_b128 v[210:213], v150 offset:20480
	ds_read_b128 v[214:217], v253 offset:20480
	ds_read_b128 v[218:221], v150 offset:22528
	ds_read_b128 v[222:225], v253 offset:22528
	global_load_lds_dwordx4 v[154:155], off
	s_add_i32 m0, s76, 0x2000
	s_add_u32 s76, s48, 0x40000
	v_lshl_add_u64 v[226:227], s[48:49], 0, v[128:129]
	s_addc_u32 s77, s49, 0
	s_add_i32 s78, s67, s54
	global_load_lds_dwordx4 v[226:227], off
	v_lshl_add_u64 v[228:229], s[76:77], 0, v[132:133]
	s_mov_b32 m0, s78
	v_lshl_add_u64 v[230:231], s[50:51], 0, v[130:131]
	global_load_lds_dwordx4 v[228:229], off
	v_lshl_add_u64 v[228:229], s[76:77], 0, v[128:129]
	s_add_i32 m0, s78, 0x2000
	s_nop 0
	global_load_lds_dwordx4 v[228:229], off
	v_lshl_add_u64 v[228:229], s[50:51], 0, v[134:135]
	s_mov_b32 m0, s57
	s_nop 0
	global_load_lds_dwordx4 v[228:229], off
	s_mov_b32 m0, s58
	s_nop 0
	global_load_lds_dwordx4 v[230:231], off
	s_waitcnt vmcnt(8)
	s_waitcnt lgkmcnt(0)
	s_barrier
	s_setprio 1
	s_waitcnt lgkmcnt(0)
	v_mfma_f32_16x16x32_bf16 v[60:63], v[160:163], v[194:197], v[60:63]
	v_mfma_f32_16x16x32_bf16 v[60:63], v[164:167], v[198:201], v[60:63]
	v_mfma_f32_16x16x32_bf16 v[52:55], v[172:175], v[198:201], v[52:55]
	v_mfma_f32_16x16x32_bf16 v[52:55], v[168:171], v[194:197], v[52:55]
	v_mfma_f32_16x16x32_bf16 v[36:39], v[168:171], v[202:205], v[36:39]
	v_mfma_f32_16x16x32_bf16 v[36:39], v[172:175], v[206:209], v[36:39]
	v_mfma_f32_16x16x32_bf16 v[44:47], v[164:167], v[206:209], v[44:47]
	v_mfma_f32_16x16x32_bf16 v[44:47], v[160:163], v[202:205], v[44:47]
	v_mfma_f32_16x16x32_bf16 v[28:31], v[160:163], v[210:213], v[28:31]
	v_mfma_f32_16x16x32_bf16 v[28:31], v[164:167], v[214:217], v[28:31]
	v_mfma_f32_16x16x32_bf16 v[20:23], v[172:175], v[214:217], v[20:23]
	v_mfma_f32_16x16x32_bf16 v[20:23], v[168:171], v[210:213], v[20:23]
	v_mfma_f32_16x16x32_bf16 v[4:7], v[168:171], v[218:221], v[4:7]
	v_mfma_f32_16x16x32_bf16 v[4:7], v[172:175], v[222:225], v[4:7]
	v_mfma_f32_16x16x32_bf16 v[12:15], v[164:167], v[222:225], v[12:15]
	v_mfma_f32_16x16x32_bf16 v[12:15], v[160:163], v[218:221], v[12:15]
	s_setprio 0
	s_setprio 1
	v_mfma_f32_16x16x32_bf16 v[56:59], v[176:179], v[194:197], v[56:59]
	v_mfma_f32_16x16x32_bf16 v[56:59], v[180:183], v[198:201], v[56:59]
	v_mfma_f32_16x16x32_bf16 v[48:51], v[190:193], v[198:201], v[48:51]
	v_mfma_f32_16x16x32_bf16 v[48:51], v[186:189], v[194:197], v[48:51]
	v_mfma_f32_16x16x32_bf16 v[32:35], v[186:189], v[202:205], v[32:35]
	v_mfma_f32_16x16x32_bf16 v[32:35], v[190:193], v[206:209], v[32:35]
	v_mfma_f32_16x16x32_bf16 v[40:43], v[180:183], v[206:209], v[40:43]
	v_mfma_f32_16x16x32_bf16 v[40:43], v[176:179], v[202:205], v[40:43]
	v_mfma_f32_16x16x32_bf16 v[24:27], v[176:179], v[210:213], v[24:27]
	v_mfma_f32_16x16x32_bf16 v[24:27], v[180:183], v[214:217], v[24:27]
	v_mfma_f32_16x16x32_bf16 v[16:19], v[190:193], v[214:217], v[16:19]
	v_mfma_f32_16x16x32_bf16 v[16:19], v[186:189], v[210:213], v[16:19]
	v_mfma_f32_16x16x32_bf16 v[0:3], v[186:189], v[218:221], v[0:3]
	v_mfma_f32_16x16x32_bf16 v[0:3], v[190:193], v[222:225], v[0:3]
	v_mfma_f32_16x16x32_bf16 v[8:11], v[180:183], v[222:225], v[8:11]
	v_mfma_f32_16x16x32_bf16 v[8:11], v[176:179], v[218:221], v[8:11]
	s_setprio 0
	s_barrier
	s_add_i32 s76, 0, 0x18000
	v_add_u32_e32 v153, s76, v147
	s_add_i32 s77, 0, 0x1c000
	ds_read_b128 v[160:163], v153
	v_xor_b32_e32 v253, 64, v153
	ds_read_b128 v[164:167], v253
	ds_read_b128 v[168:171], v153 offset:2048
	ds_read_b128 v[172:175], v253 offset:2048
	v_add_u32_e32 v153, s77, v147
	ds_read_b128 v[176:179], v153
	v_xor_b32_e32 v253, 64, v153
	ds_read_b128 v[180:183], v253
	ds_read_b128 v[186:189], v153 offset:2048
	ds_read_b128 v[190:193], v253 offset:2048
	s_add_u32 s50, s50, 0x40000
	s_addc_u32 s51, s51, 0
	s_mov_b32 m0, s59
	v_lshl_add_u64 v[232:233], s[50:51], 0, v[134:135]
	ds_read_b128 v[194:197], v150 offset:32768
	v_xor_b32_e32 v253, 64, v150
	ds_read_b128 v[198:201], v253 offset:32768
	ds_read_b128 v[202:205], v150 offset:34816
	ds_read_b128 v[206:209], v253 offset:34816
	ds_read_b128 v[210:213], v150 offset:36864
	ds_read_b128 v[214:217], v253 offset:36864
	ds_read_b128 v[218:221], v150 offset:38912
	ds_read_b128 v[222:225], v253 offset:38912
	global_load_lds_dwordx4 v[232:233], off
	v_lshl_add_u64 v[232:233], s[50:51], 0, v[130:131]
	s_mov_b32 m0, s60
	s_nop 0
	global_load_lds_dwordx4 v[232:233], off
	s_waitcnt vmcnt(8)
	s_waitcnt lgkmcnt(0)
	s_barrier
	s_setprio 1
	s_waitcnt lgkmcnt(0)
	v_mfma_f32_16x16x32_bf16 v[124:127], v[160:163], v[194:197], v[124:127]
	v_mfma_f32_16x16x32_bf16 v[124:127], v[164:167], v[198:201], v[124:127]
	v_mfma_f32_16x16x32_bf16 v[116:119], v[172:175], v[198:201], v[116:119]
	v_mfma_f32_16x16x32_bf16 v[116:119], v[168:171], v[194:197], v[116:119]
	v_mfma_f32_16x16x32_bf16 v[100:103], v[168:171], v[202:205], v[100:103]
	v_mfma_f32_16x16x32_bf16 v[100:103], v[172:175], v[206:209], v[100:103]
	v_mfma_f32_16x16x32_bf16 v[108:111], v[164:167], v[206:209], v[108:111]
	v_mfma_f32_16x16x32_bf16 v[108:111], v[160:163], v[202:205], v[108:111]
	v_mfma_f32_16x16x32_bf16 v[92:95], v[160:163], v[210:213], v[92:95]
	v_mfma_f32_16x16x32_bf16 v[92:95], v[164:167], v[214:217], v[92:95]
	v_mfma_f32_16x16x32_bf16 v[84:87], v[172:175], v[214:217], v[84:87]
	v_mfma_f32_16x16x32_bf16 v[84:87], v[168:171], v[210:213], v[84:87]
	v_mfma_f32_16x16x32_bf16 v[68:71], v[168:171], v[218:221], v[68:71]
	v_mfma_f32_16x16x32_bf16 v[68:71], v[172:175], v[222:225], v[68:71]
	v_mfma_f32_16x16x32_bf16 v[76:79], v[164:167], v[222:225], v[76:79]
	v_mfma_f32_16x16x32_bf16 v[76:79], v[160:163], v[218:221], v[76:79]
	s_setprio 0
	s_setprio 1
	v_mfma_f32_16x16x32_bf16 v[120:123], v[176:179], v[194:197], v[120:123]
	v_mfma_f32_16x16x32_bf16 v[120:123], v[180:183], v[198:201], v[120:123]
	v_mfma_f32_16x16x32_bf16 v[112:115], v[190:193], v[198:201], v[112:115]
	v_mfma_f32_16x16x32_bf16 v[112:115], v[186:189], v[194:197], v[112:115]
	v_mfma_f32_16x16x32_bf16 v[96:99], v[186:189], v[202:205], v[96:99]
	v_mfma_f32_16x16x32_bf16 v[96:99], v[190:193], v[206:209], v[96:99]
	v_mfma_f32_16x16x32_bf16 v[104:107], v[180:183], v[206:209], v[104:107]
	v_mfma_f32_16x16x32_bf16 v[104:107], v[176:179], v[202:205], v[104:107]
	v_mfma_f32_16x16x32_bf16 v[88:91], v[176:179], v[210:213], v[88:91]
	v_mfma_f32_16x16x32_bf16 v[88:91], v[180:183], v[214:217], v[88:91]
	v_mfma_f32_16x16x32_bf16 v[80:83], v[190:193], v[214:217], v[80:83]
	v_mfma_f32_16x16x32_bf16 v[80:83], v[186:189], v[210:213], v[80:83]
	v_mfma_f32_16x16x32_bf16 v[64:67], v[186:189], v[218:221], v[64:67]
	v_mfma_f32_16x16x32_bf16 v[64:67], v[190:193], v[222:225], v[64:67]
	v_mfma_f32_16x16x32_bf16 v[72:75], v[180:183], v[222:225], v[72:75]
	v_mfma_f32_16x16x32_bf16 v[72:75], v[176:179], v[218:221], v[72:75]
	s_setprio 0
	s_barrier
	v_add_u32_e32 v234, 0x21000, v151
	ds_read_b128 v[236:239], v234
	ds_read_b128 v[240:243], v234 offset:256
	ds_read_b128 v[244:247], v234 offset:512
	ds_read_b128 v[248:251], v234 offset:768
	v_add_u32_e32 v235, s27, v146
	v_mul_u32_u24_e32 v235, 0x1600, v235
	v_lshl_or_b32 v234, s69, 7, v149
	v_lshl_add_u32 v235, v234, 1, v235
	s_add_i32 s50, s76, s54
	v_lshl_add_u64 v[154:155], v[154:155], 0, s[20:21]
	s_mov_b32 m0, s50
	ds_read_b128 v[194:197], v150 offset:49152
	v_xor_b32_e32 v253, 64, v150
	ds_read_b128 v[198:201], v253 offset:49152
	ds_read_b128 v[202:205], v150 offset:51200
	ds_read_b128 v[206:209], v253 offset:51200
	ds_read_b128 v[210:213], v150 offset:53248
	ds_read_b128 v[214:217], v253 offset:53248
	ds_read_b128 v[218:221], v150 offset:55296
	ds_read_b128 v[222:225], v253 offset:55296
	global_load_lds_dwordx4 v[154:155], off
	s_add_i32 m0, s50, 0x2000
	s_add_u32 s48, s48, 0x40080
	v_lshl_add_u64 v[154:155], v[226:227], 0, s[20:21]
	s_addc_u32 s49, s49, 0
	s_add_i32 s50, s77, s54
	global_load_lds_dwordx4 v[154:155], off
	v_lshl_add_u64 v[154:155], s[48:49], 0, v[132:133]
	s_mov_b32 m0, s50
	s_nop 0
	global_load_lds_dwordx4 v[154:155], off
	v_lshl_add_u64 v[154:155], s[48:49], 0, v[128:129]
	s_add_i32 m0, s50, 0x2000
	s_nop 0
	global_load_lds_dwordx4 v[154:155], off
	v_lshl_add_u64 v[154:155], v[228:229], 0, s[20:21]
	s_mov_b32 m0, s62
	s_nop 0
	global_load_lds_dwordx4 v[154:155], off
	v_lshl_add_u64 v[154:155], v[230:231], 0, s[20:21]
	s_mov_b32 m0, s63
	s_nop 0
	global_load_lds_dwordx4 v[154:155], off
	s_waitcnt lgkmcnt(8)
	v_add_f32_e32 v236, v236, v237
	v_add_f32_e32 v238, v238, v239
	v_add_f32_e32 v240, v240, v241
	v_add_f32_e32 v242, v242, v243
	v_add_f32_e32 v244, v244, v245
	v_add_f32_e32 v246, v246, v247
	v_add_f32_e32 v248, v248, v249
	v_add_f32_e32 v250, v250, v251
	v_add_f32_e32 v236, v236, v238
	v_add_f32_e32 v240, v240, v242
	v_add_f32_e32 v244, v244, v246
	v_add_f32_e32 v248, v248, v250
	v_fmamk_f32 v236, v236, 0x3a800000, v152
	v_fmamk_f32 v240, v240, 0x3a800000, v152
	v_fmamk_f32 v244, v244, 0x3a800000, v152
	v_fmamk_f32 v248, v248, 0x3a800000, v152
	v_rsq_f32_e32 v236, v236
	v_rsq_f32_e32 v240, v240
	v_rsq_f32_e32 v244, v244
	v_rsq_f32_e32 v248, v248
	v_mul_f32_e32 v252, 0xbfb8aa3b, v236
	v_mul_f32_e32 v254, v236, v236
	v_rcp_f32_e32 v254, v254
	v_pk_mul_f32 v[120:121], v[124:125], v[120:121]
	v_pk_mul_f32 v[122:123], v[126:127], v[122:123]
	v_pk_mul_f32 v[112:113], v[116:117], v[112:113]
	v_pk_mul_f32 v[114:115], v[118:119], v[114:115]
	v_pk_mul_f32 v[124:125], v[124:125], v[252:253] op_sel_hi:[1,0]
	v_pk_mul_f32 v[126:127], v[126:127], v[252:253] op_sel_hi:[1,0]
	v_pk_mul_f32 v[116:117], v[116:117], v[252:253] op_sel_hi:[1,0]
	v_pk_mul_f32 v[118:119], v[118:119], v[252:253] op_sel_hi:[1,0]
	v_exp_f32_e32 v124, v124
	v_exp_f32_e32 v125, v125
	v_exp_f32_e32 v126, v126
	v_exp_f32_e32 v127, v127
	v_exp_f32_e32 v116, v116
	v_exp_f32_e32 v117, v117
	v_exp_f32_e32 v118, v118
	v_exp_f32_e32 v119, v119
	v_pk_fma_f32 v[124:125], v[124:125], v[254:255], v[254:255] op_sel_hi:[1,0,0]
	v_pk_fma_f32 v[126:127], v[126:127], v[254:255], v[254:255] op_sel_hi:[1,0,0]
	v_pk_fma_f32 v[116:117], v[116:117], v[254:255], v[254:255] op_sel_hi:[1,0,0]
	v_pk_fma_f32 v[118:119], v[118:119], v[254:255], v[254:255] op_sel_hi:[1,0,0]
	v_rcp_f32_e32 v124, v124
	v_rcp_f32_e32 v125, v125
	v_rcp_f32_e32 v126, v126
	v_rcp_f32_e32 v127, v127
	v_rcp_f32_e32 v116, v116
	v_rcp_f32_e32 v117, v117
	v_rcp_f32_e32 v118, v118
	v_rcp_f32_e32 v119, v119
	v_pk_mul_f32 v[120:121], v[120:121], v[124:125]
	v_pk_mul_f32 v[122:123], v[122:123], v[126:127]
	v_pk_mul_f32 v[112:113], v[112:113], v[116:117]
	v_pk_mul_f32 v[114:115], v[114:115], v[118:119]
	v_cvt_pk_bf16_f32 v120, v120, v121
	v_cvt_pk_bf16_f32 v121, v122, v123
	v_cvt_pk_bf16_f32 v122, v112, v113
	v_cvt_pk_bf16_f32 v123, v114, v115
	global_store_dwordx4 v235, v[120:123], s[14:15]
	v_add_u32_e32 v234, 0x16000, v235
	v_mul_f32_e32 v252, 0xbfb8aa3b, v240
	v_mul_f32_e32 v254, v240, v240
	v_rcp_f32_e32 v254, v254
	v_pk_mul_f32 v[104:105], v[108:109], v[104:105]
	v_pk_mul_f32 v[106:107], v[110:111], v[106:107]
	v_pk_mul_f32 v[96:97], v[100:101], v[96:97]
	v_pk_mul_f32 v[98:99], v[102:103], v[98:99]
	v_pk_mul_f32 v[108:109], v[108:109], v[252:253] op_sel_hi:[1,0]
	v_pk_mul_f32 v[110:111], v[110:111], v[252:253] op_sel_hi:[1,0]
	v_pk_mul_f32 v[100:101], v[100:101], v[252:253] op_sel_hi:[1,0]
	v_pk_mul_f32 v[102:103], v[102:103], v[252:253] op_sel_hi:[1,0]
	v_exp_f32_e32 v108, v108
	v_exp_f32_e32 v109, v109
	v_exp_f32_e32 v110, v110
	v_exp_f32_e32 v111, v111
	v_exp_f32_e32 v100, v100
	v_exp_f32_e32 v101, v101
	v_exp_f32_e32 v102, v102
	v_exp_f32_e32 v103, v103
	v_pk_fma_f32 v[108:109], v[108:109], v[254:255], v[254:255] op_sel_hi:[1,0,0]
	v_pk_fma_f32 v[110:111], v[110:111], v[254:255], v[254:255] op_sel_hi:[1,0,0]
	v_pk_fma_f32 v[100:101], v[100:101], v[254:255], v[254:255] op_sel_hi:[1,0,0]
	v_pk_fma_f32 v[102:103], v[102:103], v[254:255], v[254:255] op_sel_hi:[1,0,0]
	v_rcp_f32_e32 v108, v108
	v_rcp_f32_e32 v109, v109
	v_rcp_f32_e32 v110, v110
	v_rcp_f32_e32 v111, v111
	v_rcp_f32_e32 v100, v100
	v_rcp_f32_e32 v101, v101
	v_rcp_f32_e32 v102, v102
	v_rcp_f32_e32 v103, v103
	v_pk_mul_f32 v[104:105], v[104:105], v[108:109]
	v_pk_mul_f32 v[106:107], v[106:107], v[110:111]
	v_pk_mul_f32 v[96:97], v[96:97], v[100:101]
	v_pk_mul_f32 v[98:99], v[98:99], v[102:103]
	v_cvt_pk_bf16_f32 v104, v104, v105
	v_cvt_pk_bf16_f32 v105, v106, v107
	v_cvt_pk_bf16_f32 v106, v96, v97
	v_cvt_pk_bf16_f32 v107, v98, v99
	global_store_dwordx4 v234, v[104:107], s[14:15]
	v_add_u32_e32 v235, 0x16000, v234
	v_mul_f32_e32 v252, 0xbfb8aa3b, v244
	v_mul_f32_e32 v254, v244, v244
	v_rcp_f32_e32 v254, v254
	v_pk_mul_f32 v[88:89], v[92:93], v[88:89]
	v_pk_mul_f32 v[90:91], v[94:95], v[90:91]
	v_pk_mul_f32 v[80:81], v[84:85], v[80:81]
	v_pk_mul_f32 v[82:83], v[86:87], v[82:83]
	v_pk_mul_f32 v[92:93], v[92:93], v[252:253] op_sel_hi:[1,0]
	v_pk_mul_f32 v[94:95], v[94:95], v[252:253] op_sel_hi:[1,0]
	v_pk_mul_f32 v[84:85], v[84:85], v[252:253] op_sel_hi:[1,0]
	v_pk_mul_f32 v[86:87], v[86:87], v[252:253] op_sel_hi:[1,0]
	v_exp_f32_e32 v92, v92
	v_exp_f32_e32 v93, v93
	v_exp_f32_e32 v94, v94
	v_exp_f32_e32 v95, v95
	v_exp_f32_e32 v84, v84
	v_exp_f32_e32 v85, v85
	v_exp_f32_e32 v86, v86
	v_exp_f32_e32 v87, v87
	v_pk_fma_f32 v[92:93], v[92:93], v[254:255], v[254:255] op_sel_hi:[1,0,0]
	v_pk_fma_f32 v[94:95], v[94:95], v[254:255], v[254:255] op_sel_hi:[1,0,0]
	v_pk_fma_f32 v[84:85], v[84:85], v[254:255], v[254:255] op_sel_hi:[1,0,0]
	v_pk_fma_f32 v[86:87], v[86:87], v[254:255], v[254:255] op_sel_hi:[1,0,0]
	v_rcp_f32_e32 v92, v92
	v_rcp_f32_e32 v93, v93
	v_rcp_f32_e32 v94, v94
	v_rcp_f32_e32 v95, v95
	v_rcp_f32_e32 v84, v84
	v_rcp_f32_e32 v85, v85
	v_rcp_f32_e32 v86, v86
	v_rcp_f32_e32 v87, v87
	v_pk_mul_f32 v[88:89], v[88:89], v[92:93]
	v_pk_mul_f32 v[90:91], v[90:91], v[94:95]
	v_pk_mul_f32 v[80:81], v[80:81], v[84:85]
	v_pk_mul_f32 v[82:83], v[82:83], v[86:87]
	v_cvt_pk_bf16_f32 v88, v88, v89
	v_cvt_pk_bf16_f32 v89, v90, v91
	v_cvt_pk_bf16_f32 v90, v80, v81
	v_cvt_pk_bf16_f32 v91, v82, v83
	global_store_dwordx4 v235, v[88:91], s[14:15]
	v_add_u32_e32 v234, 0x16000, v235
	v_mul_f32_e32 v252, 0xbfb8aa3b, v248
	v_mul_f32_e32 v254, v248, v248
	v_rcp_f32_e32 v254, v254
	v_pk_mul_f32 v[72:73], v[76:77], v[72:73]
	v_pk_mul_f32 v[74:75], v[78:79], v[74:75]
	v_pk_mul_f32 v[64:65], v[68:69], v[64:65]
	v_pk_mul_f32 v[66:67], v[70:71], v[66:67]
	v_pk_mul_f32 v[76:77], v[76:77], v[252:253] op_sel_hi:[1,0]
	v_pk_mul_f32 v[78:79], v[78:79], v[252:253] op_sel_hi:[1,0]
	v_pk_mul_f32 v[68:69], v[68:69], v[252:253] op_sel_hi:[1,0]
	v_pk_mul_f32 v[70:71], v[70:71], v[252:253] op_sel_hi:[1,0]
	v_exp_f32_e32 v76, v76
	v_exp_f32_e32 v77, v77
	v_exp_f32_e32 v78, v78
	v_exp_f32_e32 v79, v79
	v_exp_f32_e32 v68, v68
	v_exp_f32_e32 v69, v69
	v_exp_f32_e32 v70, v70
	v_exp_f32_e32 v71, v71
	v_pk_fma_f32 v[76:77], v[76:77], v[254:255], v[254:255] op_sel_hi:[1,0,0]
	v_pk_fma_f32 v[78:79], v[78:79], v[254:255], v[254:255] op_sel_hi:[1,0,0]
	v_pk_fma_f32 v[68:69], v[68:69], v[254:255], v[254:255] op_sel_hi:[1,0,0]
	v_pk_fma_f32 v[70:71], v[70:71], v[254:255], v[254:255] op_sel_hi:[1,0,0]
	v_rcp_f32_e32 v76, v76
	v_rcp_f32_e32 v77, v77
	v_rcp_f32_e32 v78, v78
	v_rcp_f32_e32 v79, v79
	v_rcp_f32_e32 v68, v68
	v_rcp_f32_e32 v69, v69
	v_rcp_f32_e32 v70, v70
	v_rcp_f32_e32 v71, v71
	v_pk_mul_f32 v[72:73], v[72:73], v[76:77]
	v_pk_mul_f32 v[74:75], v[74:75], v[78:79]
	v_pk_mul_f32 v[64:65], v[64:65], v[68:69]
	v_pk_mul_f32 v[66:67], v[66:67], v[70:71]
	v_cvt_pk_bf16_f32 v72, v72, v73
	v_cvt_pk_bf16_f32 v73, v74, v75
	v_cvt_pk_bf16_f32 v74, v64, v65
	v_cvt_pk_bf16_f32 v75, v66, v67
	global_store_dwordx4 v234, v[72:75], s[14:15]
	s_waitcnt vmcnt(12)
	s_waitcnt lgkmcnt(0)
	s_barrier
	s_setprio 1
	s_waitcnt lgkmcnt(0)
	v_mfma_f32_16x16x32_bf16 v[60:63], v[160:163], v[194:197], v[60:63]
	v_mfma_f32_16x16x32_bf16 v[60:63], v[164:167], v[198:201], v[60:63]
	v_mfma_f32_16x16x32_bf16 v[52:55], v[172:175], v[198:201], v[52:55]
	v_mfma_f32_16x16x32_bf16 v[52:55], v[168:171], v[194:197], v[52:55]
	v_mfma_f32_16x16x32_bf16 v[36:39], v[168:171], v[202:205], v[36:39]
	v_mfma_f32_16x16x32_bf16 v[36:39], v[172:175], v[206:209], v[36:39]
	v_mfma_f32_16x16x32_bf16 v[44:47], v[164:167], v[206:209], v[44:47]
	v_mfma_f32_16x16x32_bf16 v[44:47], v[160:163], v[202:205], v[44:47]
	v_mfma_f32_16x16x32_bf16 v[28:31], v[160:163], v[210:213], v[28:31]
	v_mfma_f32_16x16x32_bf16 v[28:31], v[164:167], v[214:217], v[28:31]
	v_mfma_f32_16x16x32_bf16 v[20:23], v[172:175], v[214:217], v[20:23]
	v_mfma_f32_16x16x32_bf16 v[20:23], v[168:171], v[210:213], v[20:23]
	v_mfma_f32_16x16x32_bf16 v[4:7], v[168:171], v[218:221], v[4:7]
	v_mfma_f32_16x16x32_bf16 v[4:7], v[172:175], v[222:225], v[4:7]
	v_mfma_f32_16x16x32_bf16 v[12:15], v[164:167], v[222:225], v[12:15]
	v_mfma_f32_16x16x32_bf16 v[12:15], v[160:163], v[218:221], v[12:15]
	s_setprio 0
	s_setprio 1
	v_mfma_f32_16x16x32_bf16 v[56:59], v[176:179], v[194:197], v[56:59]
	v_mfma_f32_16x16x32_bf16 v[56:59], v[180:183], v[198:201], v[56:59]
	v_mfma_f32_16x16x32_bf16 v[48:51], v[190:193], v[198:201], v[48:51]
	v_mfma_f32_16x16x32_bf16 v[48:51], v[186:189], v[194:197], v[48:51]
	v_mfma_f32_16x16x32_bf16 v[32:35], v[186:189], v[202:205], v[32:35]
	v_mfma_f32_16x16x32_bf16 v[32:35], v[190:193], v[206:209], v[32:35]
	v_mfma_f32_16x16x32_bf16 v[40:43], v[180:183], v[206:209], v[40:43]
	v_mfma_f32_16x16x32_bf16 v[40:43], v[176:179], v[202:205], v[40:43]
	v_mfma_f32_16x16x32_bf16 v[24:27], v[176:179], v[210:213], v[24:27]
	v_mfma_f32_16x16x32_bf16 v[24:27], v[180:183], v[214:217], v[24:27]
	v_mfma_f32_16x16x32_bf16 v[16:19], v[190:193], v[214:217], v[16:19]
	v_mfma_f32_16x16x32_bf16 v[16:19], v[186:189], v[210:213], v[16:19]
	v_mfma_f32_16x16x32_bf16 v[0:3], v[186:189], v[218:221], v[0:3]
	v_mfma_f32_16x16x32_bf16 v[0:3], v[190:193], v[222:225], v[0:3]
	v_mfma_f32_16x16x32_bf16 v[8:11], v[180:183], v[222:225], v[8:11]
	v_mfma_f32_16x16x32_bf16 v[8:11], v[176:179], v[218:221], v[8:11]
	s_setprio 0
	s_barrier
	s_add_i32 s75, s75, 2
	s_add_u32 s73, s73, 0x100
	s_addc_u32 s74, s74, 0
	s_add_u32 s46, s46, 0x100
	s_addc_u32 s47, s47, 0

.LBB0_531:
	v_add_u32_e32 v235, 0x84000, v235
	v_add_u32_e32 v234, 0x21800, v151
	ds_read_b128 v[236:239], v234
	ds_read_b128 v[240:243], v234 offset:256
	ds_read_b128 v[244:247], v234 offset:512
	ds_read_b128 v[248:251], v234 offset:768
	s_waitcnt lgkmcnt(0)
	v_add_f32_e32 v236, v236, v237
	v_add_f32_e32 v238, v238, v239
	v_add_f32_e32 v240, v240, v241
	v_add_f32_e32 v242, v242, v243
	v_add_f32_e32 v244, v244, v245
	v_add_f32_e32 v246, v246, v247
	v_add_f32_e32 v248, v248, v249
	v_add_f32_e32 v250, v250, v251
	v_add_f32_e32 v236, v236, v238
	v_add_f32_e32 v240, v240, v242
	v_add_f32_e32 v244, v244, v246
	v_add_f32_e32 v248, v248, v250
	v_fmamk_f32 v236, v236, 0x3a800000, v152
	v_fmamk_f32 v240, v240, 0x3a800000, v152
	v_fmamk_f32 v244, v244, 0x3a800000, v152
	v_fmamk_f32 v248, v248, 0x3a800000, v152
	v_rsq_f32_e32 v236, v236
	v_rsq_f32_e32 v240, v240
	v_rsq_f32_e32 v244, v244
	v_rsq_f32_e32 v248, v248
	v_mul_f32_e32 v252, 0xbfb8aa3b, v236
	v_mul_f32_e32 v254, v236, v236
	v_rcp_f32_e32 v254, v254
	v_pk_mul_f32 v[56:57], v[60:61], v[56:57]
	v_pk_mul_f32 v[58:59], v[62:63], v[58:59]
	v_pk_mul_f32 v[48:49], v[52:53], v[48:49]
	v_pk_mul_f32 v[50:51], v[54:55], v[50:51]
	v_pk_mul_f32 v[60:61], v[60:61], v[252:253] op_sel_hi:[1,0]
	v_pk_mul_f32 v[62:63], v[62:63], v[252:253] op_sel_hi:[1,0]
	v_pk_mul_f32 v[52:53], v[52:53], v[252:253] op_sel_hi:[1,0]
	v_pk_mul_f32 v[54:55], v[54:55], v[252:253] op_sel_hi:[1,0]
	v_exp_f32_e32 v60, v60
	v_exp_f32_e32 v61, v61
	v_exp_f32_e32 v62, v62
	v_exp_f32_e32 v63, v63
	v_exp_f32_e32 v52, v52
	v_exp_f32_e32 v53, v53
	v_exp_f32_e32 v54, v54
	v_exp_f32_e32 v55, v55
	v_pk_fma_f32 v[60:61], v[60:61], v[254:255], v[254:255] op_sel_hi:[1,0,0]
	v_pk_fma_f32 v[62:63], v[62:63], v[254:255], v[254:255] op_sel_hi:[1,0,0]
	v_pk_fma_f32 v[52:53], v[52:53], v[254:255], v[254:255] op_sel_hi:[1,0,0]
	v_pk_fma_f32 v[54:55], v[54:55], v[254:255], v[254:255] op_sel_hi:[1,0,0]
	v_rcp_f32_e32 v60, v60
	v_rcp_f32_e32 v61, v61
	v_rcp_f32_e32 v62, v62
	v_rcp_f32_e32 v63, v63
	v_rcp_f32_e32 v52, v52
	v_rcp_f32_e32 v53, v53
	v_rcp_f32_e32 v54, v54
	v_rcp_f32_e32 v55, v55
	v_pk_mul_f32 v[56:57], v[56:57], v[60:61]
	v_pk_mul_f32 v[58:59], v[58:59], v[62:63]
	v_pk_mul_f32 v[48:49], v[48:49], v[52:53]
	v_pk_mul_f32 v[50:51], v[50:51], v[54:55]
	v_cvt_pk_bf16_f32 v56, v56, v57
	v_cvt_pk_bf16_f32 v57, v58, v59
	v_cvt_pk_bf16_f32 v58, v48, v49
	v_cvt_pk_bf16_f32 v59, v50, v51
	global_store_dwordx4 v235, v[56:59], s[14:15]
	v_add_u32_e32 v234, 0x16000, v235
	v_mul_f32_e32 v252, 0xbfb8aa3b, v240
	v_mul_f32_e32 v254, v240, v240
	v_rcp_f32_e32 v254, v254
	v_pk_mul_f32 v[40:41], v[44:45], v[40:41]
	v_pk_mul_f32 v[42:43], v[46:47], v[42:43]
	v_pk_mul_f32 v[32:33], v[36:37], v[32:33]
	v_pk_mul_f32 v[34:35], v[38:39], v[34:35]
	v_pk_mul_f32 v[44:45], v[44:45], v[252:253] op_sel_hi:[1,0]
	v_pk_mul_f32 v[46:47], v[46:47], v[252:253] op_sel_hi:[1,0]
	v_pk_mul_f32 v[36:37], v[36:37], v[252:253] op_sel_hi:[1,0]
	v_pk_mul_f32 v[38:39], v[38:39], v[252:253] op_sel_hi:[1,0]
	v_exp_f32_e32 v44, v44
	v_exp_f32_e32 v45, v45
	v_exp_f32_e32 v46, v46
	v_exp_f32_e32 v47, v47
	v_exp_f32_e32 v36, v36
	v_exp_f32_e32 v37, v37
	v_exp_f32_e32 v38, v38
	v_exp_f32_e32 v39, v39
	v_pk_fma_f32 v[44:45], v[44:45], v[254:255], v[254:255] op_sel_hi:[1,0,0]
	v_pk_fma_f32 v[46:47], v[46:47], v[254:255], v[254:255] op_sel_hi:[1,0,0]
	v_pk_fma_f32 v[36:37], v[36:37], v[254:255], v[254:255] op_sel_hi:[1,0,0]
	v_pk_fma_f32 v[38:39], v[38:39], v[254:255], v[254:255] op_sel_hi:[1,0,0]
	v_rcp_f32_e32 v44, v44
	v_rcp_f32_e32 v45, v45
	v_rcp_f32_e32 v46, v46
	v_rcp_f32_e32 v47, v47
	v_rcp_f32_e32 v36, v36
	v_rcp_f32_e32 v37, v37
	v_rcp_f32_e32 v38, v38
	v_rcp_f32_e32 v39, v39
	v_pk_mul_f32 v[40:41], v[40:41], v[44:45]
	v_pk_mul_f32 v[42:43], v[42:43], v[46:47]
	v_pk_mul_f32 v[32:33], v[32:33], v[36:37]
	v_pk_mul_f32 v[34:35], v[34:35], v[38:39]
	v_cvt_pk_bf16_f32 v40, v40, v41
	v_cvt_pk_bf16_f32 v41, v42, v43
	v_cvt_pk_bf16_f32 v42, v32, v33
	v_cvt_pk_bf16_f32 v43, v34, v35
	global_store_dwordx4 v234, v[40:43], s[14:15]
	v_add_u32_e32 v235, 0x16000, v234
	v_mul_f32_e32 v252, 0xbfb8aa3b, v244
	v_mul_f32_e32 v254, v244, v244
	v_rcp_f32_e32 v254, v254
	v_pk_mul_f32 v[24:25], v[28:29], v[24:25]
	v_pk_mul_f32 v[26:27], v[30:31], v[26:27]
	v_pk_mul_f32 v[16:17], v[20:21], v[16:17]
	v_pk_mul_f32 v[18:19], v[22:23], v[18:19]
	v_pk_mul_f32 v[28:29], v[28:29], v[252:253] op_sel_hi:[1,0]
	v_pk_mul_f32 v[30:31], v[30:31], v[252:253] op_sel_hi:[1,0]
	v_pk_mul_f32 v[20:21], v[20:21], v[252:253] op_sel_hi:[1,0]
	v_pk_mul_f32 v[22:23], v[22:23], v[252:253] op_sel_hi:[1,0]
	v_exp_f32_e32 v28, v28
	v_exp_f32_e32 v29, v29
	v_exp_f32_e32 v30, v30
	v_exp_f32_e32 v31, v31
	v_exp_f32_e32 v20, v20
	v_exp_f32_e32 v21, v21
	v_exp_f32_e32 v22, v22
	v_exp_f32_e32 v23, v23
	v_pk_fma_f32 v[28:29], v[28:29], v[254:255], v[254:255] op_sel_hi:[1,0,0]
	v_pk_fma_f32 v[30:31], v[30:31], v[254:255], v[254:255] op_sel_hi:[1,0,0]
	v_pk_fma_f32 v[20:21], v[20:21], v[254:255], v[254:255] op_sel_hi:[1,0,0]
	v_pk_fma_f32 v[22:23], v[22:23], v[254:255], v[254:255] op_sel_hi:[1,0,0]
	v_rcp_f32_e32 v28, v28
	v_rcp_f32_e32 v29, v29
	v_rcp_f32_e32 v30, v30
	v_rcp_f32_e32 v31, v31
	v_rcp_f32_e32 v20, v20
	v_rcp_f32_e32 v21, v21
	v_rcp_f32_e32 v22, v22
	v_rcp_f32_e32 v23, v23
	v_pk_mul_f32 v[24:25], v[24:25], v[28:29]
	v_pk_mul_f32 v[26:27], v[26:27], v[30:31]
	v_pk_mul_f32 v[16:17], v[16:17], v[20:21]
	v_pk_mul_f32 v[18:19], v[18:19], v[22:23]
	v_cvt_pk_bf16_f32 v24, v24, v25
	v_cvt_pk_bf16_f32 v25, v26, v27
	v_cvt_pk_bf16_f32 v26, v16, v17
	v_cvt_pk_bf16_f32 v27, v18, v19
	global_store_dwordx4 v235, v[24:27], s[14:15]
	v_add_u32_e32 v234, 0x16000, v235
	v_mul_f32_e32 v252, 0xbfb8aa3b, v248
	v_mul_f32_e32 v254, v248, v248
	v_rcp_f32_e32 v254, v254
	v_pk_mul_f32 v[8:9], v[12:13], v[8:9]
	v_pk_mul_f32 v[10:11], v[14:15], v[10:11]
	v_pk_mul_f32 v[0:1], v[4:5], v[0:1]
	v_pk_mul_f32 v[2:3], v[6:7], v[2:3]
	v_pk_mul_f32 v[12:13], v[12:13], v[252:253] op_sel_hi:[1,0]
	v_pk_mul_f32 v[14:15], v[14:15], v[252:253] op_sel_hi:[1,0]
	v_pk_mul_f32 v[4:5], v[4:5], v[252:253] op_sel_hi:[1,0]
	v_pk_mul_f32 v[6:7], v[6:7], v[252:253] op_sel_hi:[1,0]
	v_exp_f32_e32 v12, v12
	v_exp_f32_e32 v13, v13
	v_exp_f32_e32 v14, v14
	v_exp_f32_e32 v15, v15
	v_exp_f32_e32 v4, v4
	v_exp_f32_e32 v5, v5
	v_exp_f32_e32 v6, v6
	v_exp_f32_e32 v7, v7
	v_pk_fma_f32 v[12:13], v[12:13], v[254:255], v[254:255] op_sel_hi:[1,0,0]
	v_pk_fma_f32 v[14:15], v[14:15], v[254:255], v[254:255] op_sel_hi:[1,0,0]
	v_pk_fma_f32 v[4:5], v[4:5], v[254:255], v[254:255] op_sel_hi:[1,0,0]
	v_pk_fma_f32 v[6:7], v[6:7], v[254:255], v[254:255] op_sel_hi:[1,0,0]
	v_rcp_f32_e32 v12, v12
	v_rcp_f32_e32 v13, v13
	v_rcp_f32_e32 v14, v14
	v_rcp_f32_e32 v15, v15
	v_rcp_f32_e32 v4, v4
	v_rcp_f32_e32 v5, v5
	v_rcp_f32_e32 v6, v6
	v_rcp_f32_e32 v7, v7
	v_pk_mul_f32 v[8:9], v[8:9], v[12:13]
	v_pk_mul_f32 v[10:11], v[10:11], v[14:15]
	v_pk_mul_f32 v[0:1], v[0:1], v[4:5]
	v_pk_mul_f32 v[2:3], v[2:3], v[6:7]
	v_cvt_pk_bf16_f32 v8, v8, v9
	v_cvt_pk_bf16_f32 v9, v10, v11
	v_cvt_pk_bf16_f32 v10, v0, v1
	v_cvt_pk_bf16_f32 v11, v2, v3
	global_store_dwordx4 v234, v[8:11], s[14:15]
	s_andn2_b64 vcc, exec, s[10:11]
	s_mov_b64 s[10:11], -1
	s_cbranch_vccnz .LBB0_522
	s_andn2_b64 vcc, exec, s[12:13]
	s_cbranch_vccnz .LBB0_521
	s_barrier
	s_branch .LBB0_521

.Llast_10:
	v_add_u32_e32 v153, s61, v147
	ds_read_b128 v[160:163], v153
	v_xor_b32_e32 v253, 64, v153
	ds_read_b128 v[164:167], v253
	ds_read_b128 v[168:171], v153 offset:2048
	ds_read_b128 v[172:175], v253 offset:2048
	v_add_u32_e32 v153, s62, v147
	ds_read_b128 v[176:179], v153
	v_xor_b32_e32 v253, 64, v153
	ds_read_b128 v[180:183], v253
	ds_read_b128 v[184:187], v153 offset:2048
	ds_read_b128 v[188:191], v253 offset:2048
	s_add_u32 s46, s30, 0xfffc0080
	s_addc_u32 s47, s31, -1
	s_and_b64 s[44:45], s[44:45], exec
	s_cselect_b32 s47, s25, s47
	s_cselect_b32 s46, s65, s46
	s_cselect_b32 s45, s66, s69
	s_cselect_b32 s44, s67, s68
	v_lshl_add_u64 v[154:155], s[30:31], 0, v[138:139]
	s_add_i32 m0, s52, 0xc000
	ds_read_b128 v[192:195], v150
	v_xor_b32_e32 v253, 64, v150
	ds_read_b128 v[196:199], v253
	ds_read_b128 v[200:203], v150 offset:2048
	ds_read_b128 v[204:207], v253 offset:2048
	ds_read_b128 v[208:211], v150 offset:4096
	ds_read_b128 v[212:215], v253 offset:4096
	ds_read_b128 v[216:219], v150 offset:6144
	ds_read_b128 v[220:223], v253 offset:6144
	global_load_lds_dwordx4 v[154:155], off
	v_lshl_add_u64 v[154:155], s[30:31], 0, v[136:137]
	s_add_i32 m0, s52, 0xe000
	s_nop 0
	global_load_lds_dwordx4 v[154:155], off
	s_waitcnt vmcnt(8)
	s_waitcnt lgkmcnt(0)
	s_barrier
	s_setprio 1
	s_waitcnt lgkmcnt(0)
	v_mfma_f32_16x16x32_bf16 v[124:127], v[160:163], v[192:195], v[124:127]
	v_mfma_f32_16x16x32_bf16 v[124:127], v[164:167], v[196:199], v[124:127]
	v_mfma_f32_16x16x32_bf16 v[116:119], v[172:175], v[196:199], v[116:119]
	v_mfma_f32_16x16x32_bf16 v[116:119], v[168:171], v[192:195], v[116:119]
	v_mfma_f32_16x16x32_bf16 v[100:103], v[168:171], v[200:203], v[100:103]
	v_mfma_f32_16x16x32_bf16 v[100:103], v[172:175], v[204:207], v[100:103]
	v_mfma_f32_16x16x32_bf16 v[108:111], v[164:167], v[204:207], v[108:111]
	v_mfma_f32_16x16x32_bf16 v[108:111], v[160:163], v[200:203], v[108:111]
	v_mfma_f32_16x16x32_bf16 v[92:95], v[160:163], v[208:211], v[92:95]
	v_mfma_f32_16x16x32_bf16 v[92:95], v[164:167], v[212:215], v[92:95]
	v_mfma_f32_16x16x32_bf16 v[84:87], v[172:175], v[212:215], v[84:87]
	v_mfma_f32_16x16x32_bf16 v[84:87], v[168:171], v[208:211], v[84:87]
	v_mfma_f32_16x16x32_bf16 v[68:71], v[168:171], v[216:219], v[68:71]
	v_mfma_f32_16x16x32_bf16 v[68:71], v[172:175], v[220:223], v[68:71]
	v_mfma_f32_16x16x32_bf16 v[76:79], v[164:167], v[220:223], v[76:79]
	v_mfma_f32_16x16x32_bf16 v[76:79], v[160:163], v[216:219], v[76:79]
	s_setprio 0
	s_setprio 1
	v_mfma_f32_16x16x32_bf16 v[120:123], v[176:179], v[192:195], v[120:123]
	v_mfma_f32_16x16x32_bf16 v[120:123], v[180:183], v[196:199], v[120:123]
	v_mfma_f32_16x16x32_bf16 v[112:115], v[188:191], v[196:199], v[112:115]
	v_mfma_f32_16x16x32_bf16 v[112:115], v[184:187], v[192:195], v[112:115]
	v_mfma_f32_16x16x32_bf16 v[96:99], v[184:187], v[200:203], v[96:99]
	v_mfma_f32_16x16x32_bf16 v[96:99], v[188:191], v[204:207], v[96:99]
	v_mfma_f32_16x16x32_bf16 v[104:107], v[180:183], v[204:207], v[104:107]
	v_mfma_f32_16x16x32_bf16 v[104:107], v[176:179], v[200:203], v[104:107]
	v_mfma_f32_16x16x32_bf16 v[88:91], v[176:179], v[208:211], v[88:91]
	v_mfma_f32_16x16x32_bf16 v[88:91], v[180:183], v[212:215], v[88:91]
	v_mfma_f32_16x16x32_bf16 v[80:83], v[188:191], v[212:215], v[80:83]
	v_mfma_f32_16x16x32_bf16 v[80:83], v[184:187], v[208:211], v[80:83]
	v_mfma_f32_16x16x32_bf16 v[64:67], v[184:187], v[216:219], v[64:67]
	v_mfma_f32_16x16x32_bf16 v[64:67], v[188:191], v[220:223], v[64:67]
	v_mfma_f32_16x16x32_bf16 v[72:75], v[180:183], v[220:223], v[72:75]
	v_mfma_f32_16x16x32_bf16 v[72:75], v[176:179], v[216:219], v[72:75]
	s_setprio 0
	s_barrier
	s_add_i32 s71, s61, s49
	v_lshl_add_u64 v[154:155], s[44:45], 0, v[132:133]
	s_mov_b32 m0, s71
	ds_read_b128 v[192:195], v150 offset:16384
	v_xor_b32_e32 v253, 64, v150
	ds_read_b128 v[196:199], v253 offset:16384
	ds_read_b128 v[200:203], v150 offset:18432
	ds_read_b128 v[204:207], v253 offset:18432
	ds_read_b128 v[208:211], v150 offset:20480
	ds_read_b128 v[212:215], v253 offset:20480
	ds_read_b128 v[216:219], v150 offset:22528
	ds_read_b128 v[220:223], v253 offset:22528
	global_load_lds_dwordx4 v[154:155], off
	s_add_i32 m0, s71, 0x2000
	s_add_u32 s72, s44, 0x40000
	v_lshl_add_u64 v[224:225], s[44:45], 0, v[128:129]
	s_addc_u32 s73, s45, 0
	s_add_i32 s71, s62, s49
	global_load_lds_dwordx4 v[224:225], off
	v_lshl_add_u64 v[226:227], s[72:73], 0, v[132:133]
	s_mov_b32 m0, s71
	v_lshl_add_u64 v[228:229], s[46:47], 0, v[130:131]
	global_load_lds_dwordx4 v[226:227], off
	v_lshl_add_u64 v[226:227], s[72:73], 0, v[128:129]
	s_add_i32 m0, s71, 0x2000
	s_nop 0
	global_load_lds_dwordx4 v[226:227], off
	v_lshl_add_u64 v[226:227], s[46:47], 0, v[134:135]
	s_mov_b32 m0, s52
	s_nop 0
	global_load_lds_dwordx4 v[226:227], off
	s_mov_b32 m0, s53
	s_nop 0
	global_load_lds_dwordx4 v[228:229], off
	s_waitcnt vmcnt(8)
	s_waitcnt lgkmcnt(0)
	s_barrier
	s_setprio 1
	s_waitcnt lgkmcnt(0)
	v_mfma_f32_16x16x32_bf16 v[60:63], v[160:163], v[192:195], v[60:63]
	v_mfma_f32_16x16x32_bf16 v[60:63], v[164:167], v[196:199], v[60:63]
	v_mfma_f32_16x16x32_bf16 v[52:55], v[172:175], v[196:199], v[52:55]
	v_mfma_f32_16x16x32_bf16 v[52:55], v[168:171], v[192:195], v[52:55]
	v_mfma_f32_16x16x32_bf16 v[36:39], v[168:171], v[200:203], v[36:39]
	v_mfma_f32_16x16x32_bf16 v[36:39], v[172:175], v[204:207], v[36:39]
	v_mfma_f32_16x16x32_bf16 v[44:47], v[164:167], v[204:207], v[44:47]
	v_mfma_f32_16x16x32_bf16 v[44:47], v[160:163], v[200:203], v[44:47]
	v_mfma_f32_16x16x32_bf16 v[28:31], v[160:163], v[208:211], v[28:31]
	v_mfma_f32_16x16x32_bf16 v[28:31], v[164:167], v[212:215], v[28:31]
	v_mfma_f32_16x16x32_bf16 v[20:23], v[172:175], v[212:215], v[20:23]
	v_mfma_f32_16x16x32_bf16 v[20:23], v[168:171], v[208:211], v[20:23]
	v_mfma_f32_16x16x32_bf16 v[4:7], v[168:171], v[216:219], v[4:7]
	v_mfma_f32_16x16x32_bf16 v[4:7], v[172:175], v[220:223], v[4:7]
	v_mfma_f32_16x16x32_bf16 v[12:15], v[164:167], v[220:223], v[12:15]
	v_mfma_f32_16x16x32_bf16 v[12:15], v[160:163], v[216:219], v[12:15]
	s_setprio 0
	s_setprio 1
	v_mfma_f32_16x16x32_bf16 v[56:59], v[176:179], v[192:195], v[56:59]
	v_mfma_f32_16x16x32_bf16 v[56:59], v[180:183], v[196:199], v[56:59]
	v_mfma_f32_16x16x32_bf16 v[48:51], v[188:191], v[196:199], v[48:51]
	v_mfma_f32_16x16x32_bf16 v[48:51], v[184:187], v[192:195], v[48:51]
	v_mfma_f32_16x16x32_bf16 v[32:35], v[184:187], v[200:203], v[32:35]
	v_mfma_f32_16x16x32_bf16 v[32:35], v[188:191], v[204:207], v[32:35]
	v_mfma_f32_16x16x32_bf16 v[40:43], v[180:183], v[204:207], v[40:43]
	v_mfma_f32_16x16x32_bf16 v[40:43], v[176:179], v[200:203], v[40:43]
	v_mfma_f32_16x16x32_bf16 v[24:27], v[176:179], v[208:211], v[24:27]
	v_mfma_f32_16x16x32_bf16 v[24:27], v[180:183], v[212:215], v[24:27]
	v_mfma_f32_16x16x32_bf16 v[16:19], v[188:191], v[212:215], v[16:19]
	v_mfma_f32_16x16x32_bf16 v[16:19], v[184:187], v[208:211], v[16:19]
	v_mfma_f32_16x16x32_bf16 v[0:3], v[184:187], v[216:219], v[0:3]
	v_mfma_f32_16x16x32_bf16 v[0:3], v[188:191], v[220:223], v[0:3]
	v_mfma_f32_16x16x32_bf16 v[8:11], v[180:183], v[220:223], v[8:11]
	v_mfma_f32_16x16x32_bf16 v[8:11], v[176:179], v[216:219], v[8:11]
	s_setprio 0
	s_barrier
	s_add_i32 s71, 0, 0x18000
	v_add_u32_e32 v153, s71, v147
	s_add_i32 s72, 0, 0x1c000
	ds_read_b128 v[160:163], v153
	v_xor_b32_e32 v253, 64, v153
	ds_read_b128 v[164:167], v253
	ds_read_b128 v[168:171], v153 offset:2048
	ds_read_b128 v[172:175], v253 offset:2048
	v_add_u32_e32 v153, s72, v147
	ds_read_b128 v[176:179], v153
	v_xor_b32_e32 v253, 64, v153
	ds_read_b128 v[180:183], v253
	ds_read_b128 v[184:187], v153 offset:2048
	ds_read_b128 v[188:191], v253 offset:2048
	s_add_u32 s46, s46, 0x40000
	s_addc_u32 s47, s47, 0
	s_mov_b32 m0, s54
	v_lshl_add_u64 v[230:231], s[46:47], 0, v[134:135]
	ds_read_b128 v[192:195], v150 offset:32768
	v_xor_b32_e32 v253, 64, v150
	ds_read_b128 v[196:199], v253 offset:32768
	ds_read_b128 v[200:203], v150 offset:34816
	ds_read_b128 v[204:207], v253 offset:34816
	ds_read_b128 v[208:211], v150 offset:36864
	ds_read_b128 v[212:215], v253 offset:36864
	ds_read_b128 v[216:219], v150 offset:38912
	ds_read_b128 v[220:223], v253 offset:38912
	global_load_lds_dwordx4 v[230:231], off
	v_lshl_add_u64 v[230:231], s[46:47], 0, v[130:131]
	s_mov_b32 m0, s55
	s_nop 0
	global_load_lds_dwordx4 v[230:231], off
	s_waitcnt vmcnt(8)
	s_waitcnt lgkmcnt(0)
	s_barrier
	s_setprio 1
	s_waitcnt lgkmcnt(0)
	v_mfma_f32_16x16x32_bf16 v[124:127], v[160:163], v[192:195], v[124:127]
	v_mfma_f32_16x16x32_bf16 v[124:127], v[164:167], v[196:199], v[124:127]
	v_mfma_f32_16x16x32_bf16 v[116:119], v[172:175], v[196:199], v[116:119]
	v_mfma_f32_16x16x32_bf16 v[116:119], v[168:171], v[192:195], v[116:119]
	v_mfma_f32_16x16x32_bf16 v[100:103], v[168:171], v[200:203], v[100:103]
	v_mfma_f32_16x16x32_bf16 v[100:103], v[172:175], v[204:207], v[100:103]
	v_mfma_f32_16x16x32_bf16 v[108:111], v[164:167], v[204:207], v[108:111]
	v_mfma_f32_16x16x32_bf16 v[108:111], v[160:163], v[200:203], v[108:111]
	v_mfma_f32_16x16x32_bf16 v[92:95], v[160:163], v[208:211], v[92:95]
	v_mfma_f32_16x16x32_bf16 v[92:95], v[164:167], v[212:215], v[92:95]
	v_mfma_f32_16x16x32_bf16 v[84:87], v[172:175], v[212:215], v[84:87]
	v_mfma_f32_16x16x32_bf16 v[84:87], v[168:171], v[208:211], v[84:87]
	v_mfma_f32_16x16x32_bf16 v[68:71], v[168:171], v[216:219], v[68:71]
	v_mfma_f32_16x16x32_bf16 v[68:71], v[172:175], v[220:223], v[68:71]
	v_mfma_f32_16x16x32_bf16 v[76:79], v[164:167], v[220:223], v[76:79]
	v_mfma_f32_16x16x32_bf16 v[76:79], v[160:163], v[216:219], v[76:79]
	s_setprio 0
	s_setprio 1
	v_mfma_f32_16x16x32_bf16 v[120:123], v[176:179], v[192:195], v[120:123]
	v_mfma_f32_16x16x32_bf16 v[120:123], v[180:183], v[196:199], v[120:123]
	v_mfma_f32_16x16x32_bf16 v[112:115], v[188:191], v[196:199], v[112:115]
	v_mfma_f32_16x16x32_bf16 v[112:115], v[184:187], v[192:195], v[112:115]
	v_mfma_f32_16x16x32_bf16 v[96:99], v[184:187], v[200:203], v[96:99]
	v_mfma_f32_16x16x32_bf16 v[96:99], v[188:191], v[204:207], v[96:99]
	v_mfma_f32_16x16x32_bf16 v[104:107], v[180:183], v[204:207], v[104:107]
	v_mfma_f32_16x16x32_bf16 v[104:107], v[176:179], v[200:203], v[104:107]
	v_mfma_f32_16x16x32_bf16 v[88:91], v[176:179], v[208:211], v[88:91]
	v_mfma_f32_16x16x32_bf16 v[88:91], v[180:183], v[212:215], v[88:91]
	v_mfma_f32_16x16x32_bf16 v[80:83], v[188:191], v[212:215], v[80:83]
	v_mfma_f32_16x16x32_bf16 v[80:83], v[184:187], v[208:211], v[80:83]
	v_mfma_f32_16x16x32_bf16 v[64:67], v[184:187], v[216:219], v[64:67]
	v_mfma_f32_16x16x32_bf16 v[64:67], v[188:191], v[220:223], v[64:67]
	v_mfma_f32_16x16x32_bf16 v[72:75], v[180:183], v[220:223], v[72:75]
	v_mfma_f32_16x16x32_bf16 v[72:75], v[176:179], v[216:219], v[72:75]
	s_setprio 0
	s_barrier
	v_add_u32_e32 v234, 0x21000, v151
	ds_read_b128 v[236:239], v234
	ds_read_b128 v[240:243], v234 offset:256
	ds_read_b128 v[244:247], v234 offset:512
	ds_read_b128 v[248:251], v234 offset:768
	v_add_u32_e32 v235, s23, v146
	v_mul_u32_u24_e32 v235, 0x1600, v235
	v_lshl_or_b32 v234, s64, 7, v149
	v_lshl_add_u32 v235, v234, 1, v235
	s_add_i32 s46, s71, s49
	v_lshl_add_u64 v[154:155], v[154:155], 0, s[14:15]
	s_mov_b32 m0, s46
	ds_read_b128 v[192:195], v150 offset:49152
	v_xor_b32_e32 v253, 64, v150
	ds_read_b128 v[196:199], v253 offset:49152
	ds_read_b128 v[200:203], v150 offset:51200
	ds_read_b128 v[204:207], v253 offset:51200
	ds_read_b128 v[208:211], v150 offset:53248
	ds_read_b128 v[212:215], v253 offset:53248
	ds_read_b128 v[216:219], v150 offset:55296
	ds_read_b128 v[220:223], v253 offset:55296
	global_load_lds_dwordx4 v[154:155], off
	s_add_i32 m0, s46, 0x2000
	s_add_u32 s44, s44, 0x40080
	v_lshl_add_u64 v[154:155], v[224:225], 0, s[14:15]
	s_addc_u32 s45, s45, 0
	s_add_i32 s46, s72, s49
	global_load_lds_dwordx4 v[154:155], off
	v_lshl_add_u64 v[154:155], s[44:45], 0, v[132:133]
	s_mov_b32 m0, s46
	s_nop 0
	global_load_lds_dwordx4 v[154:155], off
	v_lshl_add_u64 v[154:155], s[44:45], 0, v[128:129]
	s_add_i32 m0, s46, 0x2000
	s_nop 0
	global_load_lds_dwordx4 v[154:155], off
	v_lshl_add_u64 v[154:155], v[226:227], 0, s[14:15]
	s_mov_b32 m0, s57
	s_nop 0
	global_load_lds_dwordx4 v[154:155], off
	v_lshl_add_u64 v[154:155], v[228:229], 0, s[14:15]
	s_mov_b32 m0, s58
	s_nop 0
	global_load_lds_dwordx4 v[154:155], off
	s_waitcnt lgkmcnt(8)
	v_add_f32_e32 v236, v236, v237
	v_add_f32_e32 v238, v238, v239
	v_add_f32_e32 v240, v240, v241
	v_add_f32_e32 v242, v242, v243
	v_add_f32_e32 v244, v244, v245
	v_add_f32_e32 v246, v246, v247
	v_add_f32_e32 v248, v248, v249
	v_add_f32_e32 v250, v250, v251
	v_add_f32_e32 v236, v236, v238
	v_add_f32_e32 v240, v240, v242
	v_add_f32_e32 v244, v244, v246
	v_add_f32_e32 v248, v248, v250
	v_fmamk_f32 v236, v236, 0x3a800000, v152
	v_fmamk_f32 v240, v240, 0x3a800000, v152
	v_fmamk_f32 v244, v244, 0x3a800000, v152
	v_fmamk_f32 v248, v248, 0x3a800000, v152
	v_rsq_f32_e32 v236, v236
	v_rsq_f32_e32 v240, v240
	v_rsq_f32_e32 v244, v244
	v_rsq_f32_e32 v248, v248
	v_mul_f32_e32 v252, 0xbfb8aa3b, v236
	v_mul_f32_e32 v254, v236, v236
	v_rcp_f32_e32 v254, v254
	v_pk_mul_f32 v[120:121], v[124:125], v[120:121]
	v_pk_mul_f32 v[122:123], v[126:127], v[122:123]
	v_pk_mul_f32 v[112:113], v[116:117], v[112:113]
	v_pk_mul_f32 v[114:115], v[118:119], v[114:115]
	v_pk_mul_f32 v[124:125], v[124:125], v[252:253] op_sel_hi:[1,0]
	v_pk_mul_f32 v[126:127], v[126:127], v[252:253] op_sel_hi:[1,0]
	v_pk_mul_f32 v[116:117], v[116:117], v[252:253] op_sel_hi:[1,0]
	v_pk_mul_f32 v[118:119], v[118:119], v[252:253] op_sel_hi:[1,0]
	v_exp_f32_e32 v124, v124
	v_exp_f32_e32 v125, v125
	v_exp_f32_e32 v126, v126
	v_exp_f32_e32 v127, v127
	v_exp_f32_e32 v116, v116
	v_exp_f32_e32 v117, v117
	v_exp_f32_e32 v118, v118
	v_exp_f32_e32 v119, v119
	v_pk_fma_f32 v[124:125], v[124:125], v[254:255], v[254:255] op_sel_hi:[1,0,0]
	v_pk_fma_f32 v[126:127], v[126:127], v[254:255], v[254:255] op_sel_hi:[1,0,0]
	v_pk_fma_f32 v[116:117], v[116:117], v[254:255], v[254:255] op_sel_hi:[1,0,0]
	v_pk_fma_f32 v[118:119], v[118:119], v[254:255], v[254:255] op_sel_hi:[1,0,0]
	v_rcp_f32_e32 v124, v124
	v_rcp_f32_e32 v125, v125
	v_rcp_f32_e32 v126, v126
	v_rcp_f32_e32 v127, v127
	v_rcp_f32_e32 v116, v116
	v_rcp_f32_e32 v117, v117
	v_rcp_f32_e32 v118, v118
	v_rcp_f32_e32 v119, v119
	v_pk_mul_f32 v[120:121], v[120:121], v[124:125]
	v_pk_mul_f32 v[122:123], v[122:123], v[126:127]
	v_pk_mul_f32 v[112:113], v[112:113], v[116:117]
	v_pk_mul_f32 v[114:115], v[114:115], v[118:119]
	v_cvt_pk_bf16_f32 v120, v120, v121
	v_cvt_pk_bf16_f32 v121, v122, v123
	v_cvt_pk_bf16_f32 v122, v112, v113
	v_cvt_pk_bf16_f32 v123, v114, v115
	global_store_dwordx4 v235, v[120:123], s[10:11]
	v_add_u32_e32 v234, 0x16000, v235
	v_mul_f32_e32 v252, 0xbfb8aa3b, v240
	v_mul_f32_e32 v254, v240, v240
	v_rcp_f32_e32 v254, v254
	v_pk_mul_f32 v[104:105], v[108:109], v[104:105]
	v_pk_mul_f32 v[106:107], v[110:111], v[106:107]
	v_pk_mul_f32 v[96:97], v[100:101], v[96:97]
	v_pk_mul_f32 v[98:99], v[102:103], v[98:99]
	v_pk_mul_f32 v[108:109], v[108:109], v[252:253] op_sel_hi:[1,0]
	v_pk_mul_f32 v[110:111], v[110:111], v[252:253] op_sel_hi:[1,0]
	v_pk_mul_f32 v[100:101], v[100:101], v[252:253] op_sel_hi:[1,0]
	v_pk_mul_f32 v[102:103], v[102:103], v[252:253] op_sel_hi:[1,0]
	v_exp_f32_e32 v108, v108
	v_exp_f32_e32 v109, v109
	v_exp_f32_e32 v110, v110
	v_exp_f32_e32 v111, v111
	v_exp_f32_e32 v100, v100
	v_exp_f32_e32 v101, v101
	v_exp_f32_e32 v102, v102
	v_exp_f32_e32 v103, v103
	v_pk_fma_f32 v[108:109], v[108:109], v[254:255], v[254:255] op_sel_hi:[1,0,0]
	v_pk_fma_f32 v[110:111], v[110:111], v[254:255], v[254:255] op_sel_hi:[1,0,0]
	v_pk_fma_f32 v[100:101], v[100:101], v[254:255], v[254:255] op_sel_hi:[1,0,0]
	v_pk_fma_f32 v[102:103], v[102:103], v[254:255], v[254:255] op_sel_hi:[1,0,0]
	v_rcp_f32_e32 v108, v108
	v_rcp_f32_e32 v109, v109
	v_rcp_f32_e32 v110, v110
	v_rcp_f32_e32 v111, v111
	v_rcp_f32_e32 v100, v100
	v_rcp_f32_e32 v101, v101
	v_rcp_f32_e32 v102, v102
	v_rcp_f32_e32 v103, v103
	v_pk_mul_f32 v[104:105], v[104:105], v[108:109]
	v_pk_mul_f32 v[106:107], v[106:107], v[110:111]
	v_pk_mul_f32 v[96:97], v[96:97], v[100:101]
	v_pk_mul_f32 v[98:99], v[98:99], v[102:103]
	v_cvt_pk_bf16_f32 v104, v104, v105
	v_cvt_pk_bf16_f32 v105, v106, v107
	v_cvt_pk_bf16_f32 v106, v96, v97
	v_cvt_pk_bf16_f32 v107, v98, v99
	global_store_dwordx4 v234, v[104:107], s[10:11]
	v_add_u32_e32 v235, 0x16000, v234
	v_mul_f32_e32 v252, 0xbfb8aa3b, v244
	v_mul_f32_e32 v254, v244, v244
	v_rcp_f32_e32 v254, v254
	v_pk_mul_f32 v[88:89], v[92:93], v[88:89]
	v_pk_mul_f32 v[90:91], v[94:95], v[90:91]
	v_pk_mul_f32 v[80:81], v[84:85], v[80:81]
	v_pk_mul_f32 v[82:83], v[86:87], v[82:83]
	v_pk_mul_f32 v[92:93], v[92:93], v[252:253] op_sel_hi:[1,0]
	v_pk_mul_f32 v[94:95], v[94:95], v[252:253] op_sel_hi:[1,0]
	v_pk_mul_f32 v[84:85], v[84:85], v[252:253] op_sel_hi:[1,0]
	v_pk_mul_f32 v[86:87], v[86:87], v[252:253] op_sel_hi:[1,0]
	v_exp_f32_e32 v92, v92
	v_exp_f32_e32 v93, v93
	v_exp_f32_e32 v94, v94
	v_exp_f32_e32 v95, v95
	v_exp_f32_e32 v84, v84
	v_exp_f32_e32 v85, v85
	v_exp_f32_e32 v86, v86
	v_exp_f32_e32 v87, v87
	v_pk_fma_f32 v[92:93], v[92:93], v[254:255], v[254:255] op_sel_hi:[1,0,0]
	v_pk_fma_f32 v[94:95], v[94:95], v[254:255], v[254:255] op_sel_hi:[1,0,0]
	v_pk_fma_f32 v[84:85], v[84:85], v[254:255], v[254:255] op_sel_hi:[1,0,0]
	v_pk_fma_f32 v[86:87], v[86:87], v[254:255], v[254:255] op_sel_hi:[1,0,0]
	v_rcp_f32_e32 v92, v92
	v_rcp_f32_e32 v93, v93
	v_rcp_f32_e32 v94, v94
	v_rcp_f32_e32 v95, v95
	v_rcp_f32_e32 v84, v84
	v_rcp_f32_e32 v85, v85
	v_rcp_f32_e32 v86, v86
	v_rcp_f32_e32 v87, v87
	v_pk_mul_f32 v[88:89], v[88:89], v[92:93]
	v_pk_mul_f32 v[90:91], v[90:91], v[94:95]
	v_pk_mul_f32 v[80:81], v[80:81], v[84:85]
	v_pk_mul_f32 v[82:83], v[82:83], v[86:87]
	v_cvt_pk_bf16_f32 v88, v88, v89
	v_cvt_pk_bf16_f32 v89, v90, v91
	v_cvt_pk_bf16_f32 v90, v80, v81
	v_cvt_pk_bf16_f32 v91, v82, v83
	global_store_dwordx4 v235, v[88:91], s[10:11]
	v_add_u32_e32 v234, 0x16000, v235
	v_mul_f32_e32 v252, 0xbfb8aa3b, v248
	v_mul_f32_e32 v254, v248, v248
	v_rcp_f32_e32 v254, v254
	v_pk_mul_f32 v[72:73], v[76:77], v[72:73]
	v_pk_mul_f32 v[74:75], v[78:79], v[74:75]
	v_pk_mul_f32 v[64:65], v[68:69], v[64:65]
	v_pk_mul_f32 v[66:67], v[70:71], v[66:67]
	v_pk_mul_f32 v[76:77], v[76:77], v[252:253] op_sel_hi:[1,0]
	v_pk_mul_f32 v[78:79], v[78:79], v[252:253] op_sel_hi:[1,0]
	v_pk_mul_f32 v[68:69], v[68:69], v[252:253] op_sel_hi:[1,0]
	v_pk_mul_f32 v[70:71], v[70:71], v[252:253] op_sel_hi:[1,0]
	v_exp_f32_e32 v76, v76
	v_exp_f32_e32 v77, v77
	v_exp_f32_e32 v78, v78
	v_exp_f32_e32 v79, v79
	v_exp_f32_e32 v68, v68
	v_exp_f32_e32 v69, v69
	v_exp_f32_e32 v70, v70
	v_exp_f32_e32 v71, v71
	v_pk_fma_f32 v[76:77], v[76:77], v[254:255], v[254:255] op_sel_hi:[1,0,0]
	v_pk_fma_f32 v[78:79], v[78:79], v[254:255], v[254:255] op_sel_hi:[1,0,0]
	v_pk_fma_f32 v[68:69], v[68:69], v[254:255], v[254:255] op_sel_hi:[1,0,0]
	v_pk_fma_f32 v[70:71], v[70:71], v[254:255], v[254:255] op_sel_hi:[1,0,0]
	v_rcp_f32_e32 v76, v76
	v_rcp_f32_e32 v77, v77
	v_rcp_f32_e32 v78, v78
	v_rcp_f32_e32 v79, v79
	v_rcp_f32_e32 v68, v68
	v_rcp_f32_e32 v69, v69
	v_rcp_f32_e32 v70, v70
	v_rcp_f32_e32 v71, v71
	v_pk_mul_f32 v[72:73], v[72:73], v[76:77]
	v_pk_mul_f32 v[74:75], v[74:75], v[78:79]
	v_pk_mul_f32 v[64:65], v[64:65], v[68:69]
	v_pk_mul_f32 v[66:67], v[66:67], v[70:71]
	v_cvt_pk_bf16_f32 v72, v72, v73
	v_cvt_pk_bf16_f32 v73, v74, v75
	v_cvt_pk_bf16_f32 v74, v64, v65
	v_cvt_pk_bf16_f32 v75, v66, v67
	global_store_dwordx4 v234, v[72:75], s[10:11]
	s_waitcnt vmcnt(12)
	s_waitcnt lgkmcnt(0)
	s_barrier
	s_setprio 1
	s_waitcnt lgkmcnt(0)
	v_mfma_f32_16x16x32_bf16 v[60:63], v[160:163], v[192:195], v[60:63]
	v_mfma_f32_16x16x32_bf16 v[60:63], v[164:167], v[196:199], v[60:63]
	v_mfma_f32_16x16x32_bf16 v[52:55], v[172:175], v[196:199], v[52:55]
	v_mfma_f32_16x16x32_bf16 v[52:55], v[168:171], v[192:195], v[52:55]
	v_mfma_f32_16x16x32_bf16 v[36:39], v[168:171], v[200:203], v[36:39]
	v_mfma_f32_16x16x32_bf16 v[36:39], v[172:175], v[204:207], v[36:39]
	v_mfma_f32_16x16x32_bf16 v[44:47], v[164:167], v[204:207], v[44:47]
	v_mfma_f32_16x16x32_bf16 v[44:47], v[160:163], v[200:203], v[44:47]
	v_mfma_f32_16x16x32_bf16 v[28:31], v[160:163], v[208:211], v[28:31]
	v_mfma_f32_16x16x32_bf16 v[28:31], v[164:167], v[212:215], v[28:31]
	v_mfma_f32_16x16x32_bf16 v[20:23], v[172:175], v[212:215], v[20:23]
	v_mfma_f32_16x16x32_bf16 v[20:23], v[168:171], v[208:211], v[20:23]
	v_mfma_f32_16x16x32_bf16 v[4:7], v[168:171], v[216:219], v[4:7]
	v_mfma_f32_16x16x32_bf16 v[4:7], v[172:175], v[220:223], v[4:7]
	v_mfma_f32_16x16x32_bf16 v[12:15], v[164:167], v[220:223], v[12:15]
	v_mfma_f32_16x16x32_bf16 v[12:15], v[160:163], v[216:219], v[12:15]
	s_setprio 0
	s_setprio 1
	v_mfma_f32_16x16x32_bf16 v[56:59], v[176:179], v[192:195], v[56:59]
	v_mfma_f32_16x16x32_bf16 v[56:59], v[180:183], v[196:199], v[56:59]
	v_mfma_f32_16x16x32_bf16 v[48:51], v[188:191], v[196:199], v[48:51]
	v_mfma_f32_16x16x32_bf16 v[48:51], v[184:187], v[192:195], v[48:51]
	v_mfma_f32_16x16x32_bf16 v[32:35], v[184:187], v[200:203], v[32:35]
	v_mfma_f32_16x16x32_bf16 v[32:35], v[188:191], v[204:207], v[32:35]
	v_mfma_f32_16x16x32_bf16 v[40:43], v[180:183], v[204:207], v[40:43]
	v_mfma_f32_16x16x32_bf16 v[40:43], v[176:179], v[200:203], v[40:43]
	v_mfma_f32_16x16x32_bf16 v[24:27], v[176:179], v[208:211], v[24:27]
	v_mfma_f32_16x16x32_bf16 v[24:27], v[180:183], v[212:215], v[24:27]
	v_mfma_f32_16x16x32_bf16 v[16:19], v[188:191], v[212:215], v[16:19]
	v_mfma_f32_16x16x32_bf16 v[16:19], v[184:187], v[208:211], v[16:19]
	v_mfma_f32_16x16x32_bf16 v[0:3], v[184:187], v[216:219], v[0:3]
	v_mfma_f32_16x16x32_bf16 v[0:3], v[188:191], v[220:223], v[0:3]
	v_mfma_f32_16x16x32_bf16 v[8:11], v[180:183], v[220:223], v[8:11]
	v_mfma_f32_16x16x32_bf16 v[8:11], v[176:179], v[216:219], v[8:11]
	s_setprio 0
	s_barrier
	s_add_i32 s70, s70, 2
	s_add_u32 s68, s68, 0x100
	s_addc_u32 s69, s69, 0
	s_add_u32 s30, s30, 0x100
	s_addc_u32 s31, s31, 0

.LBB0_1102:
	v_add_u32_e32 v235, 0x84000, v235
	v_add_u32_e32 v234, 0x21800, v151
	ds_read_b128 v[236:239], v234
	ds_read_b128 v[240:243], v234 offset:256
	ds_read_b128 v[244:247], v234 offset:512
	ds_read_b128 v[248:251], v234 offset:768
	s_waitcnt lgkmcnt(0)
	v_add_f32_e32 v236, v236, v237
	v_add_f32_e32 v238, v238, v239
	v_add_f32_e32 v240, v240, v241
	v_add_f32_e32 v242, v242, v243
	v_add_f32_e32 v244, v244, v245
	v_add_f32_e32 v246, v246, v247
	v_add_f32_e32 v248, v248, v249
	v_add_f32_e32 v250, v250, v251
	v_add_f32_e32 v236, v236, v238
	v_add_f32_e32 v240, v240, v242
	v_add_f32_e32 v244, v244, v246
	v_add_f32_e32 v248, v248, v250
	v_fmamk_f32 v236, v236, 0x3a800000, v152
	v_fmamk_f32 v240, v240, 0x3a800000, v152
	v_fmamk_f32 v244, v244, 0x3a800000, v152
	v_fmamk_f32 v248, v248, 0x3a800000, v152
	v_rsq_f32_e32 v236, v236
	v_rsq_f32_e32 v240, v240
	v_rsq_f32_e32 v244, v244
	v_rsq_f32_e32 v248, v248
	v_mul_f32_e32 v252, 0xbfb8aa3b, v236
	v_mul_f32_e32 v254, v236, v236
	v_rcp_f32_e32 v254, v254
	v_pk_mul_f32 v[56:57], v[60:61], v[56:57]
	v_pk_mul_f32 v[58:59], v[62:63], v[58:59]
	v_pk_mul_f32 v[48:49], v[52:53], v[48:49]
	v_pk_mul_f32 v[50:51], v[54:55], v[50:51]
	v_pk_mul_f32 v[60:61], v[60:61], v[252:253] op_sel_hi:[1,0]
	v_pk_mul_f32 v[62:63], v[62:63], v[252:253] op_sel_hi:[1,0]
	v_pk_mul_f32 v[52:53], v[52:53], v[252:253] op_sel_hi:[1,0]
	v_pk_mul_f32 v[54:55], v[54:55], v[252:253] op_sel_hi:[1,0]
	v_exp_f32_e32 v60, v60
	v_exp_f32_e32 v61, v61
	v_exp_f32_e32 v62, v62
	v_exp_f32_e32 v63, v63
	v_exp_f32_e32 v52, v52
	v_exp_f32_e32 v53, v53
	v_exp_f32_e32 v54, v54
	v_exp_f32_e32 v55, v55
	v_pk_fma_f32 v[60:61], v[60:61], v[254:255], v[254:255] op_sel_hi:[1,0,0]
	v_pk_fma_f32 v[62:63], v[62:63], v[254:255], v[254:255] op_sel_hi:[1,0,0]
	v_pk_fma_f32 v[52:53], v[52:53], v[254:255], v[254:255] op_sel_hi:[1,0,0]
	v_pk_fma_f32 v[54:55], v[54:55], v[254:255], v[254:255] op_sel_hi:[1,0,0]
	v_rcp_f32_e32 v60, v60
	v_rcp_f32_e32 v61, v61
	v_rcp_f32_e32 v62, v62
	v_rcp_f32_e32 v63, v63
	v_rcp_f32_e32 v52, v52
	v_rcp_f32_e32 v53, v53
	v_rcp_f32_e32 v54, v54
	v_rcp_f32_e32 v55, v55
	v_pk_mul_f32 v[56:57], v[56:57], v[60:61]
	v_pk_mul_f32 v[58:59], v[58:59], v[62:63]
	v_pk_mul_f32 v[48:49], v[48:49], v[52:53]
	v_pk_mul_f32 v[50:51], v[50:51], v[54:55]
	v_cvt_pk_bf16_f32 v56, v56, v57
	v_cvt_pk_bf16_f32 v57, v58, v59
	v_cvt_pk_bf16_f32 v58, v48, v49
	v_cvt_pk_bf16_f32 v59, v50, v51
	global_store_dwordx4 v235, v[56:59], s[10:11]
	v_add_u32_e32 v234, 0x16000, v235
	v_mul_f32_e32 v252, 0xbfb8aa3b, v240
	v_mul_f32_e32 v254, v240, v240
	v_rcp_f32_e32 v254, v254
	v_pk_mul_f32 v[40:41], v[44:45], v[40:41]
	v_pk_mul_f32 v[42:43], v[46:47], v[42:43]
	v_pk_mul_f32 v[32:33], v[36:37], v[32:33]
	v_pk_mul_f32 v[34:35], v[38:39], v[34:35]
	v_pk_mul_f32 v[44:45], v[44:45], v[252:253] op_sel_hi:[1,0]
	v_pk_mul_f32 v[46:47], v[46:47], v[252:253] op_sel_hi:[1,0]
	v_pk_mul_f32 v[36:37], v[36:37], v[252:253] op_sel_hi:[1,0]
	v_pk_mul_f32 v[38:39], v[38:39], v[252:253] op_sel_hi:[1,0]
	v_exp_f32_e32 v44, v44
	v_exp_f32_e32 v45, v45
	v_exp_f32_e32 v46, v46
	v_exp_f32_e32 v47, v47
	v_exp_f32_e32 v36, v36
	v_exp_f32_e32 v37, v37
	v_exp_f32_e32 v38, v38
	v_exp_f32_e32 v39, v39
	v_pk_fma_f32 v[44:45], v[44:45], v[254:255], v[254:255] op_sel_hi:[1,0,0]
	v_pk_fma_f32 v[46:47], v[46:47], v[254:255], v[254:255] op_sel_hi:[1,0,0]
	v_pk_fma_f32 v[36:37], v[36:37], v[254:255], v[254:255] op_sel_hi:[1,0,0]
	v_pk_fma_f32 v[38:39], v[38:39], v[254:255], v[254:255] op_sel_hi:[1,0,0]
	v_rcp_f32_e32 v44, v44
	v_rcp_f32_e32 v45, v45
	v_rcp_f32_e32 v46, v46
	v_rcp_f32_e32 v47, v47
	v_rcp_f32_e32 v36, v36
	v_rcp_f32_e32 v37, v37
	v_rcp_f32_e32 v38, v38
	v_rcp_f32_e32 v39, v39
	v_pk_mul_f32 v[40:41], v[40:41], v[44:45]
	v_pk_mul_f32 v[42:43], v[42:43], v[46:47]
	v_pk_mul_f32 v[32:33], v[32:33], v[36:37]
	v_pk_mul_f32 v[34:35], v[34:35], v[38:39]
	v_cvt_pk_bf16_f32 v40, v40, v41
	v_cvt_pk_bf16_f32 v41, v42, v43
	v_cvt_pk_bf16_f32 v42, v32, v33
	v_cvt_pk_bf16_f32 v43, v34, v35
	global_store_dwordx4 v234, v[40:43], s[10:11]
	v_add_u32_e32 v235, 0x16000, v234
	v_mul_f32_e32 v252, 0xbfb8aa3b, v244
	v_mul_f32_e32 v254, v244, v244
	v_rcp_f32_e32 v254, v254
	v_pk_mul_f32 v[24:25], v[28:29], v[24:25]
	v_pk_mul_f32 v[26:27], v[30:31], v[26:27]
	v_pk_mul_f32 v[16:17], v[20:21], v[16:17]
	v_pk_mul_f32 v[18:19], v[22:23], v[18:19]
	v_pk_mul_f32 v[28:29], v[28:29], v[252:253] op_sel_hi:[1,0]
	v_pk_mul_f32 v[30:31], v[30:31], v[252:253] op_sel_hi:[1,0]
	v_pk_mul_f32 v[20:21], v[20:21], v[252:253] op_sel_hi:[1,0]
	v_pk_mul_f32 v[22:23], v[22:23], v[252:253] op_sel_hi:[1,0]
	v_exp_f32_e32 v28, v28
	v_exp_f32_e32 v29, v29
	v_exp_f32_e32 v30, v30
	v_exp_f32_e32 v31, v31
	v_exp_f32_e32 v20, v20
	v_exp_f32_e32 v21, v21
	v_exp_f32_e32 v22, v22
	v_exp_f32_e32 v23, v23
	v_pk_fma_f32 v[28:29], v[28:29], v[254:255], v[254:255] op_sel_hi:[1,0,0]
	v_pk_fma_f32 v[30:31], v[30:31], v[254:255], v[254:255] op_sel_hi:[1,0,0]
	v_pk_fma_f32 v[20:21], v[20:21], v[254:255], v[254:255] op_sel_hi:[1,0,0]
	v_pk_fma_f32 v[22:23], v[22:23], v[254:255], v[254:255] op_sel_hi:[1,0,0]
	v_rcp_f32_e32 v28, v28
	v_rcp_f32_e32 v29, v29
	v_rcp_f32_e32 v30, v30
	v_rcp_f32_e32 v31, v31
	v_rcp_f32_e32 v20, v20
	v_rcp_f32_e32 v21, v21
	v_rcp_f32_e32 v22, v22
	v_rcp_f32_e32 v23, v23
	v_pk_mul_f32 v[24:25], v[24:25], v[28:29]
	v_pk_mul_f32 v[26:27], v[26:27], v[30:31]
	v_pk_mul_f32 v[16:17], v[16:17], v[20:21]
	v_pk_mul_f32 v[18:19], v[18:19], v[22:23]
	v_cvt_pk_bf16_f32 v24, v24, v25
	v_cvt_pk_bf16_f32 v25, v26, v27
	v_cvt_pk_bf16_f32 v26, v16, v17
	v_cvt_pk_bf16_f32 v27, v18, v19
	global_store_dwordx4 v235, v[24:27], s[10:11]
	v_add_u32_e32 v234, 0x16000, v235
	v_mul_f32_e32 v252, 0xbfb8aa3b, v248
	v_mul_f32_e32 v254, v248, v248
	v_rcp_f32_e32 v254, v254
	v_pk_mul_f32 v[8:9], v[12:13], v[8:9]
	v_pk_mul_f32 v[10:11], v[14:15], v[10:11]
	v_pk_mul_f32 v[0:1], v[4:5], v[0:1]
	v_pk_mul_f32 v[2:3], v[6:7], v[2:3]
	v_pk_mul_f32 v[12:13], v[12:13], v[252:253] op_sel_hi:[1,0]
	v_pk_mul_f32 v[14:15], v[14:15], v[252:253] op_sel_hi:[1,0]
	v_pk_mul_f32 v[4:5], v[4:5], v[252:253] op_sel_hi:[1,0]
	v_pk_mul_f32 v[6:7], v[6:7], v[252:253] op_sel_hi:[1,0]
	v_exp_f32_e32 v12, v12
	v_exp_f32_e32 v13, v13
	v_exp_f32_e32 v14, v14
	v_exp_f32_e32 v15, v15
	v_exp_f32_e32 v4, v4
	v_exp_f32_e32 v5, v5
	v_exp_f32_e32 v6, v6
	v_exp_f32_e32 v7, v7
	v_pk_fma_f32 v[12:13], v[12:13], v[254:255], v[254:255] op_sel_hi:[1,0,0]
	v_pk_fma_f32 v[14:15], v[14:15], v[254:255], v[254:255] op_sel_hi:[1,0,0]
	v_pk_fma_f32 v[4:5], v[4:5], v[254:255], v[254:255] op_sel_hi:[1,0,0]
	v_pk_fma_f32 v[6:7], v[6:7], v[254:255], v[254:255] op_sel_hi:[1,0,0]
	v_rcp_f32_e32 v12, v12
	v_rcp_f32_e32 v13, v13
	v_rcp_f32_e32 v14, v14
	v_rcp_f32_e32 v15, v15
	v_rcp_f32_e32 v4, v4
	v_rcp_f32_e32 v5, v5
	v_rcp_f32_e32 v6, v6
	v_rcp_f32_e32 v7, v7
	v_pk_mul_f32 v[8:9], v[8:9], v[12:13]
	v_pk_mul_f32 v[10:11], v[10:11], v[14:15]
	v_pk_mul_f32 v[0:1], v[0:1], v[4:5]
	v_pk_mul_f32 v[2:3], v[2:3], v[6:7]
	v_cvt_pk_bf16_f32 v8, v8, v9
	v_cvt_pk_bf16_f32 v9, v10, v11
	v_cvt_pk_bf16_f32 v10, v0, v1
	v_cvt_pk_bf16_f32 v11, v2, v3
	global_store_dwordx4 v234, v[8:11], s[10:11]
	s_andn2_b64 vcc, exec, s[6:7]
	s_mov_b64 s[6:7], -1
	s_cbranch_vccnz .LBB0_1093
	s_andn2_b64 vcc, exec, s[8:9]
	s_cbranch_vccnz .LBB0_1092
	s_barrier
	s_branch .LBB0_1092
